# gemm2 loops (p/up/down) rewritten by hand: BK=64 LDS-DMA stages with full 128B lines, register-resident fragments, bf16 MFMA f32 acc unchanged; tile remap for L2
# speedup vs baseline: 1.0814x; 1.0657x over previous
; __device__ __forceinline__ int tid_() { int x = threadIdx.x; asm volatile("" : "+v"(x)); return x; }
; __device__ __forceinline__ void gemm2_stage(const bf16_t* __restrict__ A, long lda, const bf16_t* __restrict__ Bt, long ldb, int kt, char* buf, int tid) {
; #pragma unroll
;     for (int i = 0; i < 4; ++i) {
;         const int b = tid * 16 + i * 4096, r = b >> 6, c = ((b & 63) >> 4) ^ ((r >> 2) & 3);
;         __builtin_amdgcn_global_load_lds((const unsigned*)(A + (long)r * lda + kt * 32 + c * 8), (__attribute__((address_space(3))) unsigned*)(buf + b), 16, 0, 0);
;     }
; #pragma unroll
;     for (int i = 0; i < 2; ++i) {
;         const int b = tid * 16 + i * 4096, r = b >> 6, c = ((b & 63) >> 4) ^ ((r >> 2) & 3);
;         __builtin_amdgcn_global_load_lds((const unsigned*)(Bt + (long)r * ldb + kt * 32 + c * 8), (__attribute__((address_space(3))) unsigned*)(buf + 16384 + b), 16, 0, 0);
;     }
; }
; __device__ __forceinline__ void gemm_acc2(const bf16_t* __restrict__ A, long lda, const bf16_t* __restrict__ Bt, long ldb, int K, f32x4 (&acc)[8][4], char* lds) {
;     const int tid = tid_(), wid = tid >> 6, lane = tid & 63, wr = wid >> 1, wc = wid & 1, fr = lane & 15, fq = lane >> 4;
;     const int nk = K >> 5;
;     gemm2_stage(A, lda, Bt, ldb, 0, lds, tid);
;     asm volatile("s_waitcnt vmcnt(0)" ::: "memory");
;     __syncthreads();
.Lmy_up_noperm:
	s_mul_hi_u32 s0, s26, 0xba2e8c
	s_mulk_i32 s0, 0x160
	s_sub_i32 s1, s26, s0
	s_mul_hi_u32 s0, s26, 0xba2e8c
	s_and_b32 s44, s1, 7
	s_lshl_b32 s0, s0, 3
	s_add_i32 s44, s44, s0
	s_lshr_b32 s0, s1, 3
	s_mov_b32 s45, 0
	v_lshlrev_b32_e32 v235, 4, v178
	v_lshrrev_b32_e32 v236, 3, v178
	v_and_b32_e32 v237, 7, v178
	v_and_b32_e32 v232, 7, v236
	v_xor_b32_e32 v237, v237, v232
	v_lshlrev_b32_e32 v237, 4, v237
	s_movk_i32 s26, 0x800
	v_mad_u32_u24 v230, v236, s26, v237
	v_and_b32_e32 v236, 15, v178
	v_bfe_u32 v237, v178, 4, 2
	v_and_b32_e32 v232, 7, v236
	v_xor_b32_e32 v237, v237, v232
	v_lshlrev_b32_e32 v237, 4, v237
	v_lshl_or_b32 v237, v236, 7, v237
	v_bfe_u32 v236, v178, 7, 1
	v_lshl_add_u32 v231, v236, 14, v237
	v_bfe_u32 v236, v178, 6, 1
	v_lshl_add_u32 v233, v236, 13, v237
	v_add_u32_e32 v233, 0x8000, v233
	v_xor_b32_e32 v234, 64, v233
	v_xor_b32_e32 v232, 64, v231
	v_readlane_b32 s48, v241, 31
	v_readlane_b32 s49, v241, 32
	s_lshl_b32 s26, s44, 19
	s_add_u32 s48, s48, s26
	s_addc_u32 s49, s49, 0
	v_readlane_b32 s50, v241, 39
	v_readlane_b32 s51, v241, 40
	s_lshl_b32 s26, s0, 18
	s_add_u32 s50, s50, s26
	s_addc_u32 s51, s51, 0
	v_readfirstlane_b32 s28, v235
	s_nop 0
	s_add_i32 m0, s28, 0x0
	s_add_u32 s26, s48, 0x0
	s_addc_u32 s27, s49, 0
	global_load_lds_dwordx4 v230, s[26:27]
	s_add_i32 m0, s28, 0x1000
	s_add_u32 s26, s48, 0x10000
	s_addc_u32 s27, s49, 0
	global_load_lds_dwordx4 v230, s[26:27]
	s_add_i32 m0, s28, 0x2000
	s_add_u32 s26, s48, 0x20000
	s_addc_u32 s27, s49, 0
	global_load_lds_dwordx4 v230, s[26:27]
	s_add_i32 m0, s28, 0x3000
	s_add_u32 s26, s48, 0x30000
	s_addc_u32 s27, s49, 0
	global_load_lds_dwordx4 v230, s[26:27]
	s_add_i32 m0, s28, 0x4000
	s_add_u32 s26, s48, 0x40000
	s_addc_u32 s27, s49, 0
	global_load_lds_dwordx4 v230, s[26:27]
	s_add_i32 m0, s28, 0x5000
	s_add_u32 s26, s48, 0x50000
	s_addc_u32 s27, s49, 0
	global_load_lds_dwordx4 v230, s[26:27]
	s_add_i32 m0, s28, 0x6000
	s_add_u32 s26, s48, 0x60000
	s_addc_u32 s27, s49, 0
	global_load_lds_dwordx4 v230, s[26:27]
	s_add_i32 m0, s28, 0x7000
	s_add_u32 s26, s48, 0x70000
	s_addc_u32 s27, s49, 0
	global_load_lds_dwordx4 v230, s[26:27]
	s_add_i32 m0, s28, 0x8000
	s_add_u32 s26, s50, 0x0
	s_addc_u32 s27, s51, 0
	global_load_lds_dwordx4 v230, s[26:27]
	s_add_i32 m0, s28, 0x9000
	s_add_u32 s26, s50, 0x10000
	s_addc_u32 s27, s51, 0
	global_load_lds_dwordx4 v230, s[26:27]
	s_add_i32 m0, s28, 0xa000
	s_add_u32 s26, s50, 0x20000
	s_addc_u32 s27, s51, 0
	global_load_lds_dwordx4 v230, s[26:27]
	s_add_i32 m0, s28, 0xb000
	s_add_u32 s26, s50, 0x30000
	s_addc_u32 s27, s51, 0
	global_load_lds_dwordx4 v230, s[26:27]
	s_waitcnt vmcnt(12)
	v_mov_b32_e32 v2, 0
	v_mov_b32_e32 v3, 0
	v_mov_b32_e32 v4, 0
	v_mov_b32_e32 v5, 0
	v_mov_b32_e32 v6, 0
	v_mov_b32_e32 v7, 0
	v_mov_b32_e32 v8, 0
	v_mov_b32_e32 v9, 0
	v_mov_b32_e32 v10, 0
	v_mov_b32_e32 v11, 0
	v_mov_b32_e32 v12, 0
	v_mov_b32_e32 v13, 0
	v_mov_b32_e32 v14, 0
	v_mov_b32_e32 v15, 0
	v_mov_b32_e32 v16, 0
	v_mov_b32_e32 v17, 0
	v_mov_b32_e32 v18, 0
	v_mov_b32_e32 v19, 0
	v_mov_b32_e32 v20, 0
	v_mov_b32_e32 v21, 0
	v_mov_b32_e32 v22, 0
	v_mov_b32_e32 v23, 0
	v_mov_b32_e32 v24, 0
	v_mov_b32_e32 v25, 0
	v_mov_b32_e32 v26, 0
	v_mov_b32_e32 v27, 0
	v_mov_b32_e32 v28, 0
	v_mov_b32_e32 v29, 0
	v_mov_b32_e32 v30, 0
	v_mov_b32_e32 v31, 0
	v_mov_b32_e32 v32, 0
	v_mov_b32_e32 v33, 0
	v_mov_b32_e32 v34, 0
	v_mov_b32_e32 v35, 0
	v_mov_b32_e32 v36, 0
	v_mov_b32_e32 v37, 0
	v_mov_b32_e32 v38, 0
	v_mov_b32_e32 v39, 0
	v_mov_b32_e32 v40, 0
	v_mov_b32_e32 v41, 0
	v_mov_b32_e32 v42, 0
	v_mov_b32_e32 v43, 0
	v_mov_b32_e32 v44, 0
	v_mov_b32_e32 v45, 0
	v_mov_b32_e32 v46, 0
	v_mov_b32_e32 v47, 0
	v_mov_b32_e32 v48, 0
	v_mov_b32_e32 v49, 0
	v_mov_b32_e32 v50, 0
	v_mov_b32_e32 v51, 0
	v_mov_b32_e32 v52, 0
	v_mov_b32_e32 v53, 0
	v_mov_b32_e32 v54, 0
	v_mov_b32_e32 v55, 0
	v_mov_b32_e32 v56, 0
	v_mov_b32_e32 v57, 0
	v_mov_b32_e32 v58, 0
	v_mov_b32_e32 v59, 0
	v_mov_b32_e32 v60, 0
	v_mov_b32_e32 v61, 0
	v_mov_b32_e32 v62, 0
	v_mov_b32_e32 v63, 0
	v_mov_b32_e32 v64, 0
	v_mov_b32_e32 v65, 0
	v_mov_b32_e32 v66, 0
	v_mov_b32_e32 v67, 0
	v_mov_b32_e32 v68, 0
	v_mov_b32_e32 v69, 0
	v_mov_b32_e32 v70, 0
	v_mov_b32_e32 v71, 0
	v_mov_b32_e32 v72, 0
	v_mov_b32_e32 v73, 0
	v_mov_b32_e32 v74, 0
	v_mov_b32_e32 v75, 0
	v_mov_b32_e32 v76, 0
	v_mov_b32_e32 v77, 0
	v_mov_b32_e32 v78, 0
	v_mov_b32_e32 v79, 0
	v_mov_b32_e32 v80, 0
	v_mov_b32_e32 v81, 0
	v_mov_b32_e32 v82, 0
	v_mov_b32_e32 v83, 0
	v_mov_b32_e32 v84, 0
	v_mov_b32_e32 v85, 0
	v_mov_b32_e32 v86, 0
	v_mov_b32_e32 v87, 0
	v_mov_b32_e32 v88, 0
	v_mov_b32_e32 v89, 0
	v_mov_b32_e32 v90, 0
	v_mov_b32_e32 v91, 0
	v_mov_b32_e32 v92, 0
	v_mov_b32_e32 v93, 0
	v_mov_b32_e32 v94, 0
	v_mov_b32_e32 v95, 0
	v_mov_b32_e32 v96, 0
	v_mov_b32_e32 v97, 0
	v_mov_b32_e32 v98, 0
	v_mov_b32_e32 v99, 0
	v_mov_b32_e32 v100, 0
	v_mov_b32_e32 v101, 0
	v_mov_b32_e32 v102, 0
	v_mov_b32_e32 v103, 0
	v_mov_b32_e32 v104, 0
	v_mov_b32_e32 v105, 0
	v_mov_b32_e32 v106, 0
	v_mov_b32_e32 v107, 0
	v_mov_b32_e32 v108, 0
	v_mov_b32_e32 v109, 0
	v_mov_b32_e32 v110, 0
	v_mov_b32_e32 v111, 0
	v_mov_b32_e32 v112, 0
	v_mov_b32_e32 v113, 0
	v_mov_b32_e32 v114, 0
	v_mov_b32_e32 v115, 0
	v_mov_b32_e32 v116, 0
	v_mov_b32_e32 v117, 0
	v_mov_b32_e32 v118, 0
	v_mov_b32_e32 v119, 0
	v_mov_b32_e32 v120, 0
	v_mov_b32_e32 v121, 0
	v_mov_b32_e32 v122, 0
	v_mov_b32_e32 v123, 0
	v_mov_b32_e32 v124, 0
	v_mov_b32_e32 v125, 0
	v_mov_b32_e32 v126, 0
	v_mov_b32_e32 v127, 0
	v_mov_b32_e32 v128, 0
	v_mov_b32_e32 v129, 0
	s_mov_b32 s45, 0
; __device__ __forceinline__ f32x4 mfma16(bf16x8 a, bf16x8 b, f32x4 c) { return __builtin_amdgcn_mfma_f32_16x16x32_bf16(a, b, c, 0, 0, 0); }
; __device__ __forceinline__ void gemm_acc2(const bf16_t* __restrict__ A, long lda, const bf16_t* __restrict__ Bt, long ldb, int K, f32x4 (&acc)[8][4], char* lds) {
;     ...
;     for (int kt = 0; kt < nk; ++kt) {
;         char* cur = lds + (kt & 1) * 24576;
;         if (kt + 1 < nk) gemm2_stage(A, lda, Bt, ldb, kt + 1, lds + ((kt + 1) & 1) * 24576, tid);
;         bf16x8 bfr[4];
; #pragma unroll
;         for (int n = 0; n < 4; ++n) { const int row = wc * 64 + n * 16 + fr; bfr[n] = *reinterpret_cast<const bf16x8*>(cur + 16384 + row * 64 + ((fq ^ ((row >> 2) & 3)) << 4)); }
;         bf16x8 af[8];
; #pragma unroll
;         for (int m = 0; m < 8; ++m) { const int row = wr * 128 + m * 16 + fr; af[m] = *reinterpret_cast<const bf16x8*>(cur + row * 64 + ((fq ^ ((row >> 2) & 3)) << 4)); }
;         __builtin_amdgcn_s_setprio(1);
; #pragma unroll
;         for (int m = 0; m < 8; ++m)
; #pragma unroll
;             for (int n = 0; n < 4; ++n) acc[m][n] = mfma16(bfr[n], af[m], acc[m][n]);
;         __builtin_amdgcn_s_setprio(0);
;         asm volatile("s_waitcnt vmcnt(0)" ::: "memory");
;         __syncthreads();
;     }
.Lmy_up_loop:
	s_waitcnt vmcnt(0)
	s_barrier
	ds_read_b128 v[130:133], v233
	ds_read_b128 v[134:137], v233 offset:2048
	ds_read_b128 v[138:141], v233 offset:4096
	ds_read_b128 v[142:145], v233 offset:6144
	ds_read_b128 v[146:149], v234
	ds_read_b128 v[150:153], v234 offset:2048
	ds_read_b128 v[154:157], v234 offset:4096
	ds_read_b128 v[158:161], v234 offset:6144
	ds_read_b128 v[162:165], v231
	ds_read_b128 v[166:169], v231 offset:2048
	ds_read_b128 v[170:173], v231 offset:4096
	ds_read_b128 v[174:177], v231 offset:6144
	ds_read_b128 v[182:185], v231 offset:8192
	ds_read_b128 v[186:189], v231 offset:10240
	ds_read_b128 v[190:193], v231 offset:12288
	ds_read_b128 v[194:197], v231 offset:14336
	ds_read_b128 v[198:201], v232
	ds_read_b128 v[202:205], v232 offset:2048
	ds_read_b128 v[206:209], v232 offset:4096
	ds_read_b128 v[210:213], v232 offset:6144
	ds_read_b128 v[214:217], v232 offset:8192
	ds_read_b128 v[218:221], v232 offset:10240
	ds_read_b128 v[222:225], v232 offset:12288
	ds_read_b128 v[226:229], v232 offset:14336
	s_add_u32 s48, s48, 0x80
	s_addc_u32 s49, s49, 0
	s_add_u32 s50, s50, 0x80
	s_addc_u32 s51, s51, 0
	s_waitcnt lgkmcnt(0)
	s_barrier
	s_setprio 1
	v_mfma_f32_16x16x32_bf16 v[126:129], v[130:133], v[162:165], v[126:129]
	v_mfma_f32_16x16x32_bf16 v[122:125], v[134:137], v[162:165], v[122:125]
	v_mfma_f32_16x16x32_bf16 v[118:121], v[138:141], v[162:165], v[118:121]
	v_mfma_f32_16x16x32_bf16 v[114:117], v[142:145], v[162:165], v[114:117]
	s_add_i32 m0, s28, 0x0
	s_add_u32 s26, s48, 0x0
	s_addc_u32 s27, s49, 0
	global_load_lds_dwordx4 v230, s[26:27]
	v_mfma_f32_16x16x32_bf16 v[110:113], v[130:133], v[166:169], v[110:113]
	v_mfma_f32_16x16x32_bf16 v[106:109], v[134:137], v[166:169], v[106:109]
	v_mfma_f32_16x16x32_bf16 v[102:105], v[138:141], v[166:169], v[102:105]
	v_mfma_f32_16x16x32_bf16 v[98:101], v[142:145], v[166:169], v[98:101]
	s_add_i32 m0, s28, 0x1000
	s_add_u32 s26, s48, 0x10000
	s_addc_u32 s27, s49, 0
	global_load_lds_dwordx4 v230, s[26:27]
	v_mfma_f32_16x16x32_bf16 v[94:97], v[130:133], v[170:173], v[94:97]
	v_mfma_f32_16x16x32_bf16 v[90:93], v[134:137], v[170:173], v[90:93]
	v_mfma_f32_16x16x32_bf16 v[86:89], v[138:141], v[170:173], v[86:89]
	v_mfma_f32_16x16x32_bf16 v[82:85], v[142:145], v[170:173], v[82:85]
	s_add_i32 m0, s28, 0x2000
	s_add_u32 s26, s48, 0x20000
	s_addc_u32 s27, s49, 0
	global_load_lds_dwordx4 v230, s[26:27]
	v_mfma_f32_16x16x32_bf16 v[78:81], v[130:133], v[174:177], v[78:81]
	v_mfma_f32_16x16x32_bf16 v[74:77], v[134:137], v[174:177], v[74:77]
	v_mfma_f32_16x16x32_bf16 v[70:73], v[138:141], v[174:177], v[70:73]
	v_mfma_f32_16x16x32_bf16 v[66:69], v[142:145], v[174:177], v[66:69]
	s_add_i32 m0, s28, 0x3000
	s_add_u32 s26, s48, 0x30000
	s_addc_u32 s27, s49, 0
	global_load_lds_dwordx4 v230, s[26:27]
	v_mfma_f32_16x16x32_bf16 v[62:65], v[130:133], v[182:185], v[62:65]
	v_mfma_f32_16x16x32_bf16 v[58:61], v[134:137], v[182:185], v[58:61]
	v_mfma_f32_16x16x32_bf16 v[54:57], v[138:141], v[182:185], v[54:57]
	v_mfma_f32_16x16x32_bf16 v[50:53], v[142:145], v[182:185], v[50:53]
	s_add_i32 m0, s28, 0x4000
	s_add_u32 s26, s48, 0x40000
	s_addc_u32 s27, s49, 0
	global_load_lds_dwordx4 v230, s[26:27]
	v_mfma_f32_16x16x32_bf16 v[46:49], v[130:133], v[186:189], v[46:49]
	v_mfma_f32_16x16x32_bf16 v[42:45], v[134:137], v[186:189], v[42:45]
	v_mfma_f32_16x16x32_bf16 v[38:41], v[138:141], v[186:189], v[38:41]
	v_mfma_f32_16x16x32_bf16 v[34:37], v[142:145], v[186:189], v[34:37]
	s_add_i32 m0, s28, 0x5000
	s_add_u32 s26, s48, 0x50000
	s_addc_u32 s27, s49, 0
	global_load_lds_dwordx4 v230, s[26:27]
	v_mfma_f32_16x16x32_bf16 v[30:33], v[130:133], v[190:193], v[30:33]
	v_mfma_f32_16x16x32_bf16 v[26:29], v[134:137], v[190:193], v[26:29]
	v_mfma_f32_16x16x32_bf16 v[22:25], v[138:141], v[190:193], v[22:25]
	v_mfma_f32_16x16x32_bf16 v[18:21], v[142:145], v[190:193], v[18:21]
	s_add_i32 m0, s28, 0x6000
	s_add_u32 s26, s48, 0x60000
	s_addc_u32 s27, s49, 0
	global_load_lds_dwordx4 v230, s[26:27]
	v_mfma_f32_16x16x32_bf16 v[14:17], v[130:133], v[194:197], v[14:17]
	v_mfma_f32_16x16x32_bf16 v[10:13], v[134:137], v[194:197], v[10:13]
	v_mfma_f32_16x16x32_bf16 v[6:9], v[138:141], v[194:197], v[6:9]
	v_mfma_f32_16x16x32_bf16 v[2:5], v[142:145], v[194:197], v[2:5]
	s_add_i32 m0, s28, 0x7000
	s_add_u32 s26, s48, 0x70000
	s_addc_u32 s27, s49, 0
	global_load_lds_dwordx4 v230, s[26:27]
	v_mfma_f32_16x16x32_bf16 v[126:129], v[146:149], v[198:201], v[126:129]
	v_mfma_f32_16x16x32_bf16 v[122:125], v[150:153], v[198:201], v[122:125]
	v_mfma_f32_16x16x32_bf16 v[118:121], v[154:157], v[198:201], v[118:121]
	v_mfma_f32_16x16x32_bf16 v[114:117], v[158:161], v[198:201], v[114:117]
	s_add_i32 m0, s28, 0x8000
	s_add_u32 s26, s50, 0x0
	s_addc_u32 s27, s51, 0
	global_load_lds_dwordx4 v230, s[26:27]
	v_mfma_f32_16x16x32_bf16 v[110:113], v[146:149], v[202:205], v[110:113]
	v_mfma_f32_16x16x32_bf16 v[106:109], v[150:153], v[202:205], v[106:109]
	v_mfma_f32_16x16x32_bf16 v[102:105], v[154:157], v[202:205], v[102:105]
	v_mfma_f32_16x16x32_bf16 v[98:101], v[158:161], v[202:205], v[98:101]
	s_add_i32 m0, s28, 0x9000
	s_add_u32 s26, s50, 0x10000
	s_addc_u32 s27, s51, 0
	global_load_lds_dwordx4 v230, s[26:27]
	v_mfma_f32_16x16x32_bf16 v[94:97], v[146:149], v[206:209], v[94:97]
	v_mfma_f32_16x16x32_bf16 v[90:93], v[150:153], v[206:209], v[90:93]
	v_mfma_f32_16x16x32_bf16 v[86:89], v[154:157], v[206:209], v[86:89]
	v_mfma_f32_16x16x32_bf16 v[82:85], v[158:161], v[206:209], v[82:85]
	s_add_i32 m0, s28, 0xa000
	s_add_u32 s26, s50, 0x20000
	s_addc_u32 s27, s51, 0
	global_load_lds_dwordx4 v230, s[26:27]
	v_mfma_f32_16x16x32_bf16 v[78:81], v[146:149], v[210:213], v[78:81]
; __device__ __forceinline__ f32x4 mfma16(bf16x8 a, bf16x8 b, f32x4 c) { return __builtin_amdgcn_mfma_f32_16x16x32_bf16(a, b, c, 0, 0, 0); }
; __device__ __forceinline__ void gemm_acc2(const bf16_t* __restrict__ A, long lda, const bf16_t* __restrict__ Bt, long ldb, int K, f32x4 (&acc)[8][4], char* lds) {
;     ...
;     for (int kt = 0; kt < nk; ++kt) {
;         char* cur = lds + (kt & 1) * 24576;
;         if (kt + 1 < nk) gemm2_stage(A, lda, Bt, ldb, kt + 1, lds + ((kt + 1) & 1) * 24576, tid);
;         bf16x8 bfr[4];
; #pragma unroll
;         for (int n = 0; n < 4; ++n) { const int row = wc * 64 + n * 16 + fr; bfr[n] = *reinterpret_cast<const bf16x8*>(cur + 16384 + row * 64 + ((fq ^ ((row >> 2) & 3)) << 4)); }
;         bf16x8 af[8];
; #pragma unroll
;         for (int m = 0; m < 8; ++m) { const int row = wr * 128 + m * 16 + fr; af[m] = *reinterpret_cast<const bf16x8*>(cur + row * 64 + ((fq ^ ((row >> 2) & 3)) << 4)); }
;         __builtin_amdgcn_s_setprio(1);
; #pragma unroll
;         for (int m = 0; m < 8; ++m)
; #pragma unroll
;             for (int n = 0; n < 4; ++n) acc[m][n] = mfma16(bfr[n], af[m], acc[m][n]);
;         __builtin_amdgcn_s_setprio(0);
;         asm volatile("s_waitcnt vmcnt(0)" ::: "memory");
;         __syncthreads();
;     }
	v_mfma_f32_16x16x32_bf16 v[74:77], v[150:153], v[210:213], v[74:77]
	v_mfma_f32_16x16x32_bf16 v[70:73], v[154:157], v[210:213], v[70:73]
	v_mfma_f32_16x16x32_bf16 v[66:69], v[158:161], v[210:213], v[66:69]
	s_add_i32 m0, s28, 0xb000
	s_add_u32 s26, s50, 0x30000
	s_addc_u32 s27, s51, 0
	global_load_lds_dwordx4 v230, s[26:27]
	v_mfma_f32_16x16x32_bf16 v[62:65], v[146:149], v[214:217], v[62:65]
	v_mfma_f32_16x16x32_bf16 v[58:61], v[150:153], v[214:217], v[58:61]
	v_mfma_f32_16x16x32_bf16 v[54:57], v[154:157], v[214:217], v[54:57]
	v_mfma_f32_16x16x32_bf16 v[50:53], v[158:161], v[214:217], v[50:53]
	v_mfma_f32_16x16x32_bf16 v[46:49], v[146:149], v[218:221], v[46:49]
	v_mfma_f32_16x16x32_bf16 v[42:45], v[150:153], v[218:221], v[42:45]
	v_mfma_f32_16x16x32_bf16 v[38:41], v[154:157], v[218:221], v[38:41]
	v_mfma_f32_16x16x32_bf16 v[34:37], v[158:161], v[218:221], v[34:37]
	v_mfma_f32_16x16x32_bf16 v[30:33], v[146:149], v[222:225], v[30:33]
	v_mfma_f32_16x16x32_bf16 v[26:29], v[150:153], v[222:225], v[26:29]
	v_mfma_f32_16x16x32_bf16 v[22:25], v[154:157], v[222:225], v[22:25]
	v_mfma_f32_16x16x32_bf16 v[18:21], v[158:161], v[222:225], v[18:21]
	v_mfma_f32_16x16x32_bf16 v[14:17], v[146:149], v[226:229], v[14:17]
	v_mfma_f32_16x16x32_bf16 v[10:13], v[150:153], v[226:229], v[10:13]
	v_mfma_f32_16x16x32_bf16 v[6:9], v[154:157], v[226:229], v[6:9]
	v_mfma_f32_16x16x32_bf16 v[2:5], v[158:161], v[226:229], v[2:5]
	s_setprio 0
	s_add_i32 s45, s45, 1
	s_cmp_lt_u32 s45, 15
	s_cbranch_scc1 .Lmy_up_loop
	s_waitcnt vmcnt(0)
	s_barrier
	ds_read_b128 v[130:133], v233
	ds_read_b128 v[134:137], v233 offset:2048
	ds_read_b128 v[138:141], v233 offset:4096
	ds_read_b128 v[142:145], v233 offset:6144
	ds_read_b128 v[146:149], v234
	ds_read_b128 v[150:153], v234 offset:2048
	ds_read_b128 v[154:157], v234 offset:4096
	ds_read_b128 v[158:161], v234 offset:6144
	ds_read_b128 v[162:165], v231
	ds_read_b128 v[166:169], v231 offset:2048
	ds_read_b128 v[170:173], v231 offset:4096
	ds_read_b128 v[174:177], v231 offset:6144
	ds_read_b128 v[182:185], v231 offset:8192
	ds_read_b128 v[186:189], v231 offset:10240
	ds_read_b128 v[190:193], v231 offset:12288
	ds_read_b128 v[194:197], v231 offset:14336
	ds_read_b128 v[198:201], v232
	ds_read_b128 v[202:205], v232 offset:2048
	ds_read_b128 v[206:209], v232 offset:4096
	ds_read_b128 v[210:213], v232 offset:6144
	ds_read_b128 v[214:217], v232 offset:8192
	ds_read_b128 v[218:221], v232 offset:10240
	ds_read_b128 v[222:225], v232 offset:12288
	ds_read_b128 v[226:229], v232 offset:14336
	s_waitcnt lgkmcnt(0)
	s_setprio 1
	v_mfma_f32_16x16x32_bf16 v[126:129], v[130:133], v[162:165], v[126:129]
	v_mfma_f32_16x16x32_bf16 v[122:125], v[134:137], v[162:165], v[122:125]
	v_mfma_f32_16x16x32_bf16 v[118:121], v[138:141], v[162:165], v[118:121]
	v_mfma_f32_16x16x32_bf16 v[114:117], v[142:145], v[162:165], v[114:117]
	v_mfma_f32_16x16x32_bf16 v[110:113], v[130:133], v[166:169], v[110:113]
	v_mfma_f32_16x16x32_bf16 v[106:109], v[134:137], v[166:169], v[106:109]
	v_mfma_f32_16x16x32_bf16 v[102:105], v[138:141], v[166:169], v[102:105]
	v_mfma_f32_16x16x32_bf16 v[98:101], v[142:145], v[166:169], v[98:101]
	v_mfma_f32_16x16x32_bf16 v[94:97], v[130:133], v[170:173], v[94:97]
	v_mfma_f32_16x16x32_bf16 v[90:93], v[134:137], v[170:173], v[90:93]
	v_mfma_f32_16x16x32_bf16 v[86:89], v[138:141], v[170:173], v[86:89]
	v_mfma_f32_16x16x32_bf16 v[82:85], v[142:145], v[170:173], v[82:85]
	v_mfma_f32_16x16x32_bf16 v[78:81], v[130:133], v[174:177], v[78:81]
	v_mfma_f32_16x16x32_bf16 v[74:77], v[134:137], v[174:177], v[74:77]
	v_mfma_f32_16x16x32_bf16 v[70:73], v[138:141], v[174:177], v[70:73]
	v_mfma_f32_16x16x32_bf16 v[66:69], v[142:145], v[174:177], v[66:69]
	v_mfma_f32_16x16x32_bf16 v[62:65], v[130:133], v[182:185], v[62:65]
	v_mfma_f32_16x16x32_bf16 v[58:61], v[134:137], v[182:185], v[58:61]
	v_mfma_f32_16x16x32_bf16 v[54:57], v[138:141], v[182:185], v[54:57]
	v_mfma_f32_16x16x32_bf16 v[50:53], v[142:145], v[182:185], v[50:53]
	v_mfma_f32_16x16x32_bf16 v[46:49], v[130:133], v[186:189], v[46:49]
	v_mfma_f32_16x16x32_bf16 v[42:45], v[134:137], v[186:189], v[42:45]
	v_mfma_f32_16x16x32_bf16 v[38:41], v[138:141], v[186:189], v[38:41]
	v_mfma_f32_16x16x32_bf16 v[34:37], v[142:145], v[186:189], v[34:37]
	v_mfma_f32_16x16x32_bf16 v[30:33], v[130:133], v[190:193], v[30:33]
	v_mfma_f32_16x16x32_bf16 v[26:29], v[134:137], v[190:193], v[26:29]
	v_mfma_f32_16x16x32_bf16 v[22:25], v[138:141], v[190:193], v[22:25]
	v_mfma_f32_16x16x32_bf16 v[18:21], v[142:145], v[190:193], v[18:21]
	v_mfma_f32_16x16x32_bf16 v[14:17], v[130:133], v[194:197], v[14:17]
	v_mfma_f32_16x16x32_bf16 v[10:13], v[134:137], v[194:197], v[10:13]
	v_mfma_f32_16x16x32_bf16 v[6:9], v[138:141], v[194:197], v[6:9]
	v_mfma_f32_16x16x32_bf16 v[2:5], v[142:145], v[194:197], v[2:5]
	v_mfma_f32_16x16x32_bf16 v[126:129], v[146:149], v[198:201], v[126:129]
	v_mfma_f32_16x16x32_bf16 v[122:125], v[150:153], v[198:201], v[122:125]
	v_mfma_f32_16x16x32_bf16 v[118:121], v[154:157], v[198:201], v[118:121]
	v_mfma_f32_16x16x32_bf16 v[114:117], v[158:161], v[198:201], v[114:117]
	v_mfma_f32_16x16x32_bf16 v[110:113], v[146:149], v[202:205], v[110:113]
	v_mfma_f32_16x16x32_bf16 v[106:109], v[150:153], v[202:205], v[106:109]
	v_mfma_f32_16x16x32_bf16 v[102:105], v[154:157], v[202:205], v[102:105]
	v_mfma_f32_16x16x32_bf16 v[98:101], v[158:161], v[202:205], v[98:101]
	v_mfma_f32_16x16x32_bf16 v[94:97], v[146:149], v[206:209], v[94:97]
	v_mfma_f32_16x16x32_bf16 v[90:93], v[150:153], v[206:209], v[90:93]
	v_mfma_f32_16x16x32_bf16 v[86:89], v[154:157], v[206:209], v[86:89]
	v_mfma_f32_16x16x32_bf16 v[82:85], v[158:161], v[206:209], v[82:85]
; __device__ __forceinline__ int tid_() { int x = threadIdx.x; asm volatile("" : "+v"(x)); return x; }
; __device__ __forceinline__ unsigned pack2(float a, float b) { const f32x2n v = {a, b}; const bf16x2n h = __builtin_convertvector(v, bf16x2n); return __builtin_bit_cast(unsigned, h); }
; __device__ __forceinline__ void store_tile2_bf16(const f32x4 (&acc)[8][4], bf16_t* __restrict__ dst, long ld) {
;     const int tid = tid_(), wid = tid >> 6, lane = tid & 63, wr = wid >> 1, wc = wid & 1, fr = lane & 15, fq = lane >> 4;
; #pragma unroll
;     for (int m = 0; m < 8; ++m)
; #pragma unroll
;         for (int n = 0; n < 4; ++n) {
;             const f32x4 v = acc[m][n];
;             *(u32x2*)(dst + (long)(wr * 128 + m * 16 + fr) * ld + wc * 64 + n * 16 + fq * 4) = (u32x2){pack2(v[0], v[1]), pack2(v[2], v[3])};
;         }
; }
; __device__ void ph_gemm_up(const Params& P, char* lds) {
;     ...
;         store_tile2_bf16(acc, Z + (size_t)mt * 256 * 5632 + nt * 128, 5632);
	v_mfma_f32_16x16x32_bf16 v[78:81], v[146:149], v[210:213], v[78:81]
	v_mfma_f32_16x16x32_bf16 v[74:77], v[150:153], v[210:213], v[74:77]
	v_mfma_f32_16x16x32_bf16 v[70:73], v[154:157], v[210:213], v[70:73]
	v_mfma_f32_16x16x32_bf16 v[66:69], v[158:161], v[210:213], v[66:69]
	v_mfma_f32_16x16x32_bf16 v[62:65], v[146:149], v[214:217], v[62:65]
	v_mfma_f32_16x16x32_bf16 v[58:61], v[150:153], v[214:217], v[58:61]
	v_mfma_f32_16x16x32_bf16 v[54:57], v[154:157], v[214:217], v[54:57]
	v_mfma_f32_16x16x32_bf16 v[50:53], v[158:161], v[214:217], v[50:53]
	v_mfma_f32_16x16x32_bf16 v[46:49], v[146:149], v[218:221], v[46:49]
	v_mfma_f32_16x16x32_bf16 v[42:45], v[150:153], v[218:221], v[42:45]
	v_mfma_f32_16x16x32_bf16 v[38:41], v[154:157], v[218:221], v[38:41]
	v_mfma_f32_16x16x32_bf16 v[34:37], v[158:161], v[218:221], v[34:37]
	v_mfma_f32_16x16x32_bf16 v[30:33], v[146:149], v[222:225], v[30:33]
	v_mfma_f32_16x16x32_bf16 v[26:29], v[150:153], v[222:225], v[26:29]
	v_mfma_f32_16x16x32_bf16 v[22:25], v[154:157], v[222:225], v[22:25]
	v_mfma_f32_16x16x32_bf16 v[18:21], v[158:161], v[222:225], v[18:21]
	v_mfma_f32_16x16x32_bf16 v[14:17], v[146:149], v[226:229], v[14:17]
	v_mfma_f32_16x16x32_bf16 v[10:13], v[150:153], v[226:229], v[10:13]
	v_mfma_f32_16x16x32_bf16 v[6:9], v[154:157], v[226:229], v[6:9]
	v_mfma_f32_16x16x32_bf16 v[2:5], v[158:161], v[226:229], v[2:5]
	s_setprio 0
	v_mov_b32_e32 v182, 0x2c60000
	v_mov_b32_e32 v183, 0x540
	v_mov_b32_e32 v184, 0x6000
	v_mov_b32_e32 v185, 0x2000
	v_mov_b32_e32 v186, 0x160000
	v_mov_b32_e32 v187, 0x70
	v_mov_b32_e32 v188, 0x1100
	v_mov_b32_e32 v218, 0
	v_mov_b32_e32 v219, 0
	v_mov_b32_e32 v220, 0
	v_mov_b32_e32 v221, 0
	s_mul_i32 s24, s44, 0x2c0000
	s_mul_hi_i32 s1, s44, 0x2c0000
	s_add_u32 s24, s90, s24
	s_addc_u32 s26, s91, s1
	s_lshl_b32 s0, s0, 7
	s_ashr_i32 s1, s0, 31
	s_lshl_b64 s[0:1], s[0:1], 1
	v_mov_b32_e32 v134, v178
	s_waitcnt vmcnt(0)
	s_barrier
	s_add_u32 s0, s24, s0
	s_addc_u32 s1, s26, s1
	v_and_b32_e32 v0, 64, v134
	v_lshlrev_b32_e32 v0, 1, v0
	v_lshl_add_u64 v[130:131], s[0:1], 0, v[0:1]
	v_lshrrev_b32_e32 v0, 1, v134
	v_and_b32_e32 v0, 24, v0
	v_and_b32_e32 v135, 0xffffff8f, v134
	v_lshl_add_u64 v[130:131], v[130:131], 0, v[0:1]
	s_movk_i32 s24, 0x2c00
	v_mad_i64_i32 v[132:133], s[0:1], v135, s24, v[130:131]
	v_cvt_pk_bf16_f32 v114, v114, v115
	v_cvt_pk_bf16_f32 v115, v116, v117
	v_or_b32_e32 v0, 16, v135
	global_store_dwordx2 v[132:133], v[114:115], off offset:96
	v_mad_i64_i32 v[114:115], s[0:1], v0, s24, v[130:131]
	v_cvt_pk_bf16_f32 v98, v98, v99
	v_cvt_pk_bf16_f32 v99, v100, v101
	v_or_b32_e32 v0, 32, v135
	global_store_dwordx2 v[114:115], v[98:99], off offset:96
	v_mad_i64_i32 v[98:99], s[0:1], v0, s24, v[130:131]
	v_cvt_pk_bf16_f32 v82, v82, v83
	v_cvt_pk_bf16_f32 v83, v84, v85
	v_or_b32_e32 v0, 48, v135
	global_store_dwordx2 v[98:99], v[82:83], off offset:96
	v_mad_i64_i32 v[82:83], s[0:1], v0, s24, v[130:131]
	v_cvt_pk_bf16_f32 v66, v66, v67
	v_cvt_pk_bf16_f32 v67, v68, v69
	v_or_b32_e32 v0, 64, v135
	global_store_dwordx2 v[82:83], v[66:67], off offset:96
	v_mad_i64_i32 v[66:67], s[0:1], v0, s24, v[130:131]
	v_cvt_pk_bf16_f32 v50, v50, v51
	v_cvt_pk_bf16_f32 v51, v52, v53
	v_or_b32_e32 v0, 0x50, v135
	global_store_dwordx2 v[66:67], v[50:51], off offset:96
	v_mad_i64_i32 v[50:51], s[0:1], v0, s24, v[130:131]
	v_cvt_pk_bf16_f32 v34, v34, v35
	v_cvt_pk_bf16_f32 v35, v36, v37
	v_or_b32_e32 v0, 0x60, v135
	global_store_dwordx2 v[50:51], v[34:35], off offset:96
	v_mad_i64_i32 v[34:35], s[0:1], v0, s24, v[130:131]
	v_cvt_pk_bf16_f32 v18, v18, v19
	v_cvt_pk_bf16_f32 v19, v20, v21
	v_or_b32_e32 v0, 0x70, v134
	global_store_dwordx2 v[34:35], v[18:19], off offset:96
	v_mad_i64_i32 v[18:19], s[0:1], v0, s24, v[130:131]
	v_readlane_b32 s0, v239, 10
	s_add_i32 s21, s21, s0
	v_cvt_pk_bf16_f32 v126, v126, v127
	v_cvt_pk_bf16_f32 v127, v128, v129
	v_cvt_pk_bf16_f32 v122, v122, v123
	v_cvt_pk_bf16_f32 v123, v124, v125
	v_cvt_pk_bf16_f32 v118, v118, v119
	v_cvt_pk_bf16_f32 v119, v120, v121
	v_cvt_pk_bf16_f32 v110, v110, v111
	v_cvt_pk_bf16_f32 v111, v112, v113
	v_cvt_pk_bf16_f32 v106, v106, v107
	v_cvt_pk_bf16_f32 v107, v108, v109
	v_cvt_pk_bf16_f32 v102, v102, v103
	v_cvt_pk_bf16_f32 v103, v104, v105
	v_cvt_pk_bf16_f32 v94, v94, v95
	v_cvt_pk_bf16_f32 v95, v96, v97
	v_cvt_pk_bf16_f32 v90, v90, v91
	v_cvt_pk_bf16_f32 v91, v92, v93
	v_cvt_pk_bf16_f32 v86, v86, v87
	v_cvt_pk_bf16_f32 v87, v88, v89
	v_cvt_pk_bf16_f32 v78, v78, v79
	v_cvt_pk_bf16_f32 v79, v80, v81
	v_cvt_pk_bf16_f32 v74, v74, v75
	v_cvt_pk_bf16_f32 v75, v76, v77
	v_cvt_pk_bf16_f32 v70, v70, v71
	v_cvt_pk_bf16_f32 v71, v72, v73
	v_cvt_pk_bf16_f32 v62, v62, v63
	v_cvt_pk_bf16_f32 v63, v64, v65
	v_cvt_pk_bf16_f32 v58, v58, v59
	v_cvt_pk_bf16_f32 v59, v60, v61
	v_cvt_pk_bf16_f32 v54, v54, v55
	v_cvt_pk_bf16_f32 v55, v56, v57
	v_cvt_pk_bf16_f32 v46, v46, v47
	v_cvt_pk_bf16_f32 v47, v48, v49
	v_cvt_pk_bf16_f32 v42, v42, v43
	v_cvt_pk_bf16_f32 v43, v44, v45
	v_cvt_pk_bf16_f32 v38, v38, v39
	v_cvt_pk_bf16_f32 v39, v40, v41
	v_cvt_pk_bf16_f32 v30, v30, v31
	v_cvt_pk_bf16_f32 v31, v32, v33
	v_cvt_pk_bf16_f32 v26, v26, v27
	v_cvt_pk_bf16_f32 v27, v28, v29
	v_cvt_pk_bf16_f32 v22, v22, v23
	v_cvt_pk_bf16_f32 v23, v24, v25
	v_cvt_pk_bf16_f32 v14, v14, v15
	v_cvt_pk_bf16_f32 v15, v16, v17
	v_cvt_pk_bf16_f32 v10, v10, v11
	v_cvt_pk_bf16_f32 v11, v12, v13
	v_cvt_pk_bf16_f32 v6, v6, v7
	v_cvt_pk_bf16_f32 v7, v8, v9
	v_cvt_pk_bf16_f32 v2, v2, v3
	v_cvt_pk_bf16_f32 v3, v4, v5
	s_cmpk_gt_i32 s21, 0x15ff
	global_store_dwordx2 v[132:133], v[126:127], off
	global_store_dwordx2 v[132:133], v[122:123], off offset:32
	global_store_dwordx2 v[132:133], v[118:119], off offset:64
	global_store_dwordx2 v[114:115], v[110:111], off
	global_store_dwordx2 v[114:115], v[106:107], off offset:32
	global_store_dwordx2 v[114:115], v[102:103], off offset:64
	global_store_dwordx2 v[98:99], v[94:95], off
	global_store_dwordx2 v[98:99], v[90:91], off offset:32
	global_store_dwordx2 v[98:99], v[86:87], off offset:64
	global_store_dwordx2 v[82:83], v[78:79], off
	global_store_dwordx2 v[82:83], v[74:75], off offset:32
	global_store_dwordx2 v[82:83], v[70:71], off offset:64
	global_store_dwordx2 v[66:67], v[62:63], off
	global_store_dwordx2 v[66:67], v[58:59], off offset:32
	global_store_dwordx2 v[66:67], v[54:55], off offset:64
	global_store_dwordx2 v[50:51], v[46:47], off
	global_store_dwordx2 v[50:51], v[42:43], off offset:32
	global_store_dwordx2 v[50:51], v[38:39], off offset:64
	global_store_dwordx2 v[34:35], v[30:31], off
	global_store_dwordx2 v[34:35], v[26:27], off offset:32
	global_store_dwordx2 v[34:35], v[22:23], off offset:64
	global_store_dwordx2 v[18:19], v[14:15], off
	global_store_dwordx2 v[18:19], v[10:11], off offset:32
	global_store_dwordx2 v[18:19], v[6:7], off offset:64
	v_readlane_b32 s1, v239, 11
	global_store_dwordx2 v[18:19], v[2:3], off offset:96
	s_cbranch_scc0 .LBB0_290

; __device__ __forceinline__ int tid_() { int x = threadIdx.x; asm volatile("" : "+v"(x)); return x; }
; __device__ __forceinline__ int bid_() { int x = blockIdx.x; asm volatile("" : "+s"(x)); return x; }
; __device__ __forceinline__ void gemm2_stage(const bf16_t* __restrict__ A, long lda, const bf16_t* __restrict__ Bt, long ldb, int kt, char* buf, int tid) {
; #pragma unroll
;     for (int i = 0; i < 4; ++i) {
;         const int b = tid * 16 + i * 4096, r = b >> 6, c = ((b & 63) >> 4) ^ ((r >> 2) & 3);
;         __builtin_amdgcn_global_load_lds((const unsigned*)(A + (long)r * lda + kt * 32 + c * 8), (__attribute__((address_space(3))) unsigned*)(buf + b), 16, 0, 0);
;     }
; #pragma unroll
;     for (int i = 0; i < 2; ++i) {
;         const int b = tid * 16 + i * 4096, r = b >> 6, c = ((b & 63) >> 4) ^ ((r >> 2) & 3);
;         __builtin_amdgcn_global_load_lds((const unsigned*)(Bt + (long)r * ldb + kt * 32 + c * 8), (__attribute__((address_space(3))) unsigned*)(buf + 16384 + b), 16, 0, 0);
;     }
; }
; __device__ __forceinline__ void gemm_acc2(const bf16_t* __restrict__ A, long lda, const bf16_t* __restrict__ Bt, long ldb, int K, f32x4 (&acc)[8][4], char* lds) {
;     const int tid = tid_(), wid = tid >> 6, lane = tid & 63, wr = wid >> 1, wc = wid & 1, fr = lane & 15, fq = lane >> 4;
;     const int nk = K >> 5;
;     gemm2_stage(A, lda, Bt, ldb, 0, lds, tid);
;     asm volatile("s_waitcnt vmcnt(0)" ::: "memory");
;     __syncthreads();
; __device__ void ph_gemm_down(const Params& P, int l, char* lds) {
;     ...
;     for (int item = bid_(); item < 128 * 8; item += gridDim.x) {
;         const int mt = item / 8, nt = item % 8;
;         f32x4 acc[8][4]; zero_acc2(acc);
;         gemm_acc2(A + (size_t)mt * 256 * DFF, DFF, Wt + (size_t)nt * 128 * DFF, DFF, DFF, acc, lds);
.LBB0_375:
	v_readlane_b32 s1, v239, 10
	s_mov_b32 s29, s21
	s_cmp_lg_u32 s1, 0x200
	s_cbranch_scc1 .Lmy_down_noperm
	s_and_b32 s29, s21, 7
	s_lshl_b32 s29, s29, 6
	s_bfe_u32 s1, s21, 0x60003
	s_or_b32 s29, s29, s1
	s_andn2_b32 s1, s21, 0x1ff
	s_or_b32 s29, s29, s1
.Lmy_down_noperm:
	s_and_b32 s30, s29, 7
	s_lshr_b32 s29, s29, 3
	v_lshlrev_b32_e32 v235, 4, v178
	v_lshrrev_b32_e32 v236, 3, v178
	v_and_b32_e32 v237, 7, v178
	v_and_b32_e32 v232, 7, v236
	v_xor_b32_e32 v237, v237, v232
	v_lshlrev_b32_e32 v237, 4, v237
	s_movk_i32 s26, 0x1600
	v_mad_u32_u24 v230, v236, s26, v237
	v_and_b32_e32 v236, 15, v178
	v_bfe_u32 v237, v178, 4, 2
	v_and_b32_e32 v232, 7, v236
	v_xor_b32_e32 v237, v237, v232
	v_lshlrev_b32_e32 v237, 4, v237
	v_lshl_or_b32 v237, v236, 7, v237
	v_bfe_u32 v236, v178, 7, 1
	v_lshl_add_u32 v231, v236, 14, v237
	v_bfe_u32 v236, v178, 6, 1
	v_lshl_add_u32 v233, v236, 13, v237
	v_add_u32_e32 v233, 0x8000, v233
	v_xor_b32_e32 v234, 64, v233
	v_xor_b32_e32 v232, 64, v231
	s_mul_i32 s26, s29, 0x160000
	s_add_u32 s0, s42, s26
	s_addc_u32 s1, s43, 0
	s_mul_i32 s26, s30, 0xb0000
	s_add_u32 s34, s44, s26
	s_addc_u32 s35, s45, 0
	v_readfirstlane_b32 s39, v235
	s_nop 0
	s_add_i32 m0, s39, 0x0
	s_add_u32 s26, s0, 0x0
	s_addc_u32 s27, s1, 0
	global_load_lds_dwordx4 v230, s[26:27]
	s_add_i32 m0, s39, 0x1000
	s_add_u32 s26, s0, 0x2c000
	s_addc_u32 s27, s1, 0
	global_load_lds_dwordx4 v230, s[26:27]
	s_add_i32 m0, s39, 0x2000
	s_add_u32 s26, s0, 0x58000
	s_addc_u32 s27, s1, 0
	global_load_lds_dwordx4 v230, s[26:27]
	s_add_i32 m0, s39, 0x3000
	s_add_u32 s26, s0, 0x84000
	s_addc_u32 s27, s1, 0
	global_load_lds_dwordx4 v230, s[26:27]
	s_add_i32 m0, s39, 0x4000
	s_add_u32 s26, s0, 0xb0000
	s_addc_u32 s27, s1, 0
	global_load_lds_dwordx4 v230, s[26:27]
	s_add_i32 m0, s39, 0x5000
	s_add_u32 s26, s0, 0xdc000
	s_addc_u32 s27, s1, 0
	global_load_lds_dwordx4 v230, s[26:27]
	s_add_i32 m0, s39, 0x6000
	s_add_u32 s26, s0, 0x108000
	s_addc_u32 s27, s1, 0
	global_load_lds_dwordx4 v230, s[26:27]
	s_add_i32 m0, s39, 0x7000
	s_add_u32 s26, s0, 0x134000
	s_addc_u32 s27, s1, 0
	global_load_lds_dwordx4 v230, s[26:27]
	s_add_i32 m0, s39, 0x8000
	s_add_u32 s26, s34, 0x0
	s_addc_u32 s27, s35, 0
	global_load_lds_dwordx4 v230, s[26:27]
	s_add_i32 m0, s39, 0x9000
	s_add_u32 s26, s34, 0x2c000
	s_addc_u32 s27, s35, 0
	global_load_lds_dwordx4 v230, s[26:27]
	s_add_i32 m0, s39, 0xa000
	s_add_u32 s26, s34, 0x58000
	s_addc_u32 s27, s35, 0
	global_load_lds_dwordx4 v230, s[26:27]
	s_add_i32 m0, s39, 0xb000
	s_add_u32 s26, s34, 0x84000
	s_addc_u32 s27, s35, 0
	global_load_lds_dwordx4 v230, s[26:27]
	s_waitcnt vmcnt(12)
	v_mov_b32_e32 v2, 0
	v_mov_b32_e32 v3, 0
	v_mov_b32_e32 v4, 0
	v_mov_b32_e32 v5, 0
	v_mov_b32_e32 v6, 0
	v_mov_b32_e32 v7, 0
	v_mov_b32_e32 v8, 0
	v_mov_b32_e32 v9, 0
	v_mov_b32_e32 v10, 0
	v_mov_b32_e32 v11, 0
	v_mov_b32_e32 v12, 0
	v_mov_b32_e32 v13, 0
	v_mov_b32_e32 v14, 0
	v_mov_b32_e32 v15, 0
	v_mov_b32_e32 v16, 0
	v_mov_b32_e32 v17, 0
	v_mov_b32_e32 v18, 0
	v_mov_b32_e32 v19, 0
	v_mov_b32_e32 v20, 0
	v_mov_b32_e32 v21, 0
	v_mov_b32_e32 v22, 0
	v_mov_b32_e32 v23, 0
	v_mov_b32_e32 v24, 0
	v_mov_b32_e32 v25, 0
	v_mov_b32_e32 v26, 0
	v_mov_b32_e32 v27, 0
	v_mov_b32_e32 v28, 0
	v_mov_b32_e32 v29, 0
	v_mov_b32_e32 v30, 0
	v_mov_b32_e32 v31, 0
	v_mov_b32_e32 v32, 0
	v_mov_b32_e32 v33, 0
	v_mov_b32_e32 v34, 0
	v_mov_b32_e32 v35, 0
	v_mov_b32_e32 v36, 0
	v_mov_b32_e32 v37, 0
	v_mov_b32_e32 v38, 0
	v_mov_b32_e32 v39, 0
	v_mov_b32_e32 v40, 0
	v_mov_b32_e32 v41, 0
	v_mov_b32_e32 v42, 0
	v_mov_b32_e32 v43, 0
	v_mov_b32_e32 v44, 0
	v_mov_b32_e32 v45, 0
	v_mov_b32_e32 v46, 0
	v_mov_b32_e32 v47, 0
	v_mov_b32_e32 v48, 0
	v_mov_b32_e32 v49, 0
	v_mov_b32_e32 v50, 0
	v_mov_b32_e32 v51, 0
	v_mov_b32_e32 v52, 0
	v_mov_b32_e32 v53, 0
	v_mov_b32_e32 v54, 0
	v_mov_b32_e32 v55, 0
	v_mov_b32_e32 v56, 0
	v_mov_b32_e32 v57, 0
	v_mov_b32_e32 v58, 0
	v_mov_b32_e32 v59, 0
	v_mov_b32_e32 v60, 0
	v_mov_b32_e32 v61, 0
	v_mov_b32_e32 v62, 0
	v_mov_b32_e32 v63, 0
	v_mov_b32_e32 v64, 0
	v_mov_b32_e32 v65, 0
	v_mov_b32_e32 v66, 0
	v_mov_b32_e32 v67, 0
	v_mov_b32_e32 v68, 0
	v_mov_b32_e32 v69, 0
	v_mov_b32_e32 v70, 0
	v_mov_b32_e32 v71, 0
	v_mov_b32_e32 v72, 0
	v_mov_b32_e32 v73, 0
	v_mov_b32_e32 v74, 0
	v_mov_b32_e32 v75, 0
	v_mov_b32_e32 v76, 0
	v_mov_b32_e32 v77, 0
	v_mov_b32_e32 v78, 0
	v_mov_b32_e32 v79, 0
	v_mov_b32_e32 v80, 0
	v_mov_b32_e32 v81, 0
	v_mov_b32_e32 v82, 0
	v_mov_b32_e32 v83, 0
	v_mov_b32_e32 v84, 0
	v_mov_b32_e32 v85, 0
	v_mov_b32_e32 v86, 0
	v_mov_b32_e32 v87, 0
	v_mov_b32_e32 v88, 0
	v_mov_b32_e32 v89, 0
	v_mov_b32_e32 v90, 0
	v_mov_b32_e32 v91, 0
	v_mov_b32_e32 v92, 0
	v_mov_b32_e32 v93, 0
	v_mov_b32_e32 v94, 0
	v_mov_b32_e32 v95, 0
	v_mov_b32_e32 v96, 0
	v_mov_b32_e32 v97, 0
	v_mov_b32_e32 v98, 0
	v_mov_b32_e32 v99, 0
	v_mov_b32_e32 v100, 0
	v_mov_b32_e32 v101, 0
	v_mov_b32_e32 v102, 0
	v_mov_b32_e32 v103, 0
	v_mov_b32_e32 v104, 0
	v_mov_b32_e32 v105, 0
	v_mov_b32_e32 v106, 0
	v_mov_b32_e32 v107, 0
	v_mov_b32_e32 v108, 0
	v_mov_b32_e32 v109, 0
	v_mov_b32_e32 v110, 0
	v_mov_b32_e32 v111, 0
	v_mov_b32_e32 v112, 0
	v_mov_b32_e32 v113, 0
	v_mov_b32_e32 v114, 0
	v_mov_b32_e32 v115, 0
	v_mov_b32_e32 v116, 0
	v_mov_b32_e32 v117, 0
	v_mov_b32_e32 v118, 0
	v_mov_b32_e32 v119, 0
	v_mov_b32_e32 v120, 0
	v_mov_b32_e32 v121, 0
	v_mov_b32_e32 v122, 0
	v_mov_b32_e32 v123, 0
	v_mov_b32_e32 v124, 0
	v_mov_b32_e32 v125, 0
	v_mov_b32_e32 v126, 0
	v_mov_b32_e32 v127, 0
	v_mov_b32_e32 v128, 0
	v_mov_b32_e32 v129, 0
	s_mov_b32 s38, 0
; __device__ __forceinline__ f32x4 mfma16(bf16x8 a, bf16x8 b, f32x4 c) { return __builtin_amdgcn_mfma_f32_16x16x32_bf16(a, b, c, 0, 0, 0); }
; __device__ __forceinline__ void gemm_acc2(const bf16_t* __restrict__ A, long lda, const bf16_t* __restrict__ Bt, long ldb, int K, f32x4 (&acc)[8][4], char* lds) {
;     ...
;     for (int kt = 0; kt < nk; ++kt) {
;         char* cur = lds + (kt & 1) * 24576;
;         if (kt + 1 < nk) gemm2_stage(A, lda, Bt, ldb, kt + 1, lds + ((kt + 1) & 1) * 24576, tid);
;         bf16x8 bfr[4];
; #pragma unroll
;         for (int n = 0; n < 4; ++n) { const int row = wc * 64 + n * 16 + fr; bfr[n] = *reinterpret_cast<const bf16x8*>(cur + 16384 + row * 64 + ((fq ^ ((row >> 2) & 3)) << 4)); }
;         bf16x8 af[8];
; #pragma unroll
;         for (int m = 0; m < 8; ++m) { const int row = wr * 128 + m * 16 + fr; af[m] = *reinterpret_cast<const bf16x8*>(cur + row * 64 + ((fq ^ ((row >> 2) & 3)) << 4)); }
;         __builtin_amdgcn_s_setprio(1);
; #pragma unroll
;         for (int m = 0; m < 8; ++m)
; #pragma unroll
;             for (int n = 0; n < 4; ++n) acc[m][n] = mfma16(bfr[n], af[m], acc[m][n]);
;         __builtin_amdgcn_s_setprio(0);
;         asm volatile("s_waitcnt vmcnt(0)" ::: "memory");
;         __syncthreads();
;     }
.Lmy_down_loop:
	s_waitcnt vmcnt(0)
	s_barrier
	ds_read_b128 v[130:133], v233
	ds_read_b128 v[134:137], v233 offset:2048
	ds_read_b128 v[138:141], v233 offset:4096
	ds_read_b128 v[142:145], v233 offset:6144
	ds_read_b128 v[146:149], v234
	ds_read_b128 v[150:153], v234 offset:2048
	ds_read_b128 v[154:157], v234 offset:4096
	ds_read_b128 v[158:161], v234 offset:6144
	ds_read_b128 v[162:165], v231
	ds_read_b128 v[166:169], v231 offset:2048
	ds_read_b128 v[170:173], v231 offset:4096
	ds_read_b128 v[174:177], v231 offset:6144
	ds_read_b128 v[182:185], v231 offset:8192
	ds_read_b128 v[186:189], v231 offset:10240
	ds_read_b128 v[190:193], v231 offset:12288
	ds_read_b128 v[194:197], v231 offset:14336
	ds_read_b128 v[198:201], v232
	ds_read_b128 v[202:205], v232 offset:2048
	ds_read_b128 v[206:209], v232 offset:4096
	ds_read_b128 v[210:213], v232 offset:6144
	ds_read_b128 v[214:217], v232 offset:8192
	ds_read_b128 v[218:221], v232 offset:10240
	ds_read_b128 v[222:225], v232 offset:12288
	ds_read_b128 v[226:229], v232 offset:14336
	s_add_u32 s0, s0, 0x80
	s_addc_u32 s1, s1, 0
	s_add_u32 s34, s34, 0x80
	s_addc_u32 s35, s35, 0
	s_waitcnt lgkmcnt(0)
	s_barrier
	s_setprio 1
	v_mfma_f32_16x16x32_bf16 v[126:129], v[130:133], v[162:165], v[126:129]
	v_mfma_f32_16x16x32_bf16 v[122:125], v[134:137], v[162:165], v[122:125]
	v_mfma_f32_16x16x32_bf16 v[118:121], v[138:141], v[162:165], v[118:121]
	v_mfma_f32_16x16x32_bf16 v[54:57], v[142:145], v[162:165], v[54:57]
	s_add_i32 m0, s39, 0x0
	s_add_u32 s26, s0, 0x0
	s_addc_u32 s27, s1, 0
	global_load_lds_dwordx4 v230, s[26:27]
	v_mfma_f32_16x16x32_bf16 v[114:117], v[130:133], v[166:169], v[114:117]
	v_mfma_f32_16x16x32_bf16 v[110:113], v[134:137], v[166:169], v[110:113]
	v_mfma_f32_16x16x32_bf16 v[106:109], v[138:141], v[166:169], v[106:109]
	v_mfma_f32_16x16x32_bf16 v[30:33], v[142:145], v[166:169], v[30:33]
	s_add_i32 m0, s39, 0x1000
	s_add_u32 s26, s0, 0x2c000
	s_addc_u32 s27, s1, 0
	global_load_lds_dwordx4 v230, s[26:27]
	v_mfma_f32_16x16x32_bf16 v[102:105], v[130:133], v[170:173], v[102:105]
	v_mfma_f32_16x16x32_bf16 v[98:101], v[134:137], v[170:173], v[98:101]
	v_mfma_f32_16x16x32_bf16 v[94:97], v[138:141], v[170:173], v[94:97]
	v_mfma_f32_16x16x32_bf16 v[22:25], v[142:145], v[170:173], v[22:25]
	s_add_i32 m0, s39, 0x2000
	s_add_u32 s26, s0, 0x58000
	s_addc_u32 s27, s1, 0
	global_load_lds_dwordx4 v230, s[26:27]
	v_mfma_f32_16x16x32_bf16 v[90:93], v[130:133], v[174:177], v[90:93]
	v_mfma_f32_16x16x32_bf16 v[86:89], v[134:137], v[174:177], v[86:89]
	v_mfma_f32_16x16x32_bf16 v[82:85], v[138:141], v[174:177], v[82:85]
	v_mfma_f32_16x16x32_bf16 v[18:21], v[142:145], v[174:177], v[18:21]
	s_add_i32 m0, s39, 0x3000
	s_add_u32 s26, s0, 0x84000
	s_addc_u32 s27, s1, 0
	global_load_lds_dwordx4 v230, s[26:27]
	v_mfma_f32_16x16x32_bf16 v[78:81], v[130:133], v[182:185], v[78:81]
	v_mfma_f32_16x16x32_bf16 v[74:77], v[134:137], v[182:185], v[74:77]
	v_mfma_f32_16x16x32_bf16 v[70:73], v[138:141], v[182:185], v[70:73]
	v_mfma_f32_16x16x32_bf16 v[14:17], v[142:145], v[182:185], v[14:17]
	s_add_i32 m0, s39, 0x4000
	s_add_u32 s26, s0, 0xb0000
	s_addc_u32 s27, s1, 0
	global_load_lds_dwordx4 v230, s[26:27]
	v_mfma_f32_16x16x32_bf16 v[66:69], v[130:133], v[186:189], v[66:69]
	v_mfma_f32_16x16x32_bf16 v[62:65], v[134:137], v[186:189], v[62:65]
	v_mfma_f32_16x16x32_bf16 v[58:61], v[138:141], v[186:189], v[58:61]
	v_mfma_f32_16x16x32_bf16 v[10:13], v[142:145], v[186:189], v[10:13]
	s_add_i32 m0, s39, 0x5000
	s_add_u32 s26, s0, 0xdc000
	s_addc_u32 s27, s1, 0
	global_load_lds_dwordx4 v230, s[26:27]
	v_mfma_f32_16x16x32_bf16 v[50:53], v[130:133], v[190:193], v[50:53]
	v_mfma_f32_16x16x32_bf16 v[46:49], v[134:137], v[190:193], v[46:49]
	v_mfma_f32_16x16x32_bf16 v[42:45], v[138:141], v[190:193], v[42:45]
	v_mfma_f32_16x16x32_bf16 v[6:9], v[142:145], v[190:193], v[6:9]
	s_add_i32 m0, s39, 0x6000
	s_add_u32 s26, s0, 0x108000
	s_addc_u32 s27, s1, 0
	global_load_lds_dwordx4 v230, s[26:27]
	v_mfma_f32_16x16x32_bf16 v[38:41], v[130:133], v[194:197], v[38:41]
	v_mfma_f32_16x16x32_bf16 v[34:37], v[134:137], v[194:197], v[34:37]
	v_mfma_f32_16x16x32_bf16 v[26:29], v[138:141], v[194:197], v[26:29]
	v_mfma_f32_16x16x32_bf16 v[2:5], v[142:145], v[194:197], v[2:5]
	s_add_i32 m0, s39, 0x7000
	s_add_u32 s26, s0, 0x134000
	s_addc_u32 s27, s1, 0
	global_load_lds_dwordx4 v230, s[26:27]
	v_mfma_f32_16x16x32_bf16 v[126:129], v[146:149], v[198:201], v[126:129]
	v_mfma_f32_16x16x32_bf16 v[122:125], v[150:153], v[198:201], v[122:125]
	v_mfma_f32_16x16x32_bf16 v[118:121], v[154:157], v[198:201], v[118:121]
	v_mfma_f32_16x16x32_bf16 v[54:57], v[158:161], v[198:201], v[54:57]
	s_add_i32 m0, s39, 0x8000
	s_add_u32 s26, s34, 0x0
	s_addc_u32 s27, s35, 0
	global_load_lds_dwordx4 v230, s[26:27]
	v_mfma_f32_16x16x32_bf16 v[114:117], v[146:149], v[202:205], v[114:117]
	v_mfma_f32_16x16x32_bf16 v[110:113], v[150:153], v[202:205], v[110:113]
	v_mfma_f32_16x16x32_bf16 v[106:109], v[154:157], v[202:205], v[106:109]
	v_mfma_f32_16x16x32_bf16 v[30:33], v[158:161], v[202:205], v[30:33]
	s_add_i32 m0, s39, 0x9000
	s_add_u32 s26, s34, 0x2c000
	s_addc_u32 s27, s35, 0
	global_load_lds_dwordx4 v230, s[26:27]
	v_mfma_f32_16x16x32_bf16 v[102:105], v[146:149], v[206:209], v[102:105]
	v_mfma_f32_16x16x32_bf16 v[98:101], v[150:153], v[206:209], v[98:101]
	v_mfma_f32_16x16x32_bf16 v[94:97], v[154:157], v[206:209], v[94:97]
	v_mfma_f32_16x16x32_bf16 v[22:25], v[158:161], v[206:209], v[22:25]
	s_add_i32 m0, s39, 0xa000
	s_add_u32 s26, s34, 0x58000
	s_addc_u32 s27, s35, 0
	global_load_lds_dwordx4 v230, s[26:27]
	v_mfma_f32_16x16x32_bf16 v[90:93], v[146:149], v[210:213], v[90:93]
; __device__ __forceinline__ f32x4 mfma16(bf16x8 a, bf16x8 b, f32x4 c) { return __builtin_amdgcn_mfma_f32_16x16x32_bf16(a, b, c, 0, 0, 0); }
; __device__ __forceinline__ void gemm_acc2(const bf16_t* __restrict__ A, long lda, const bf16_t* __restrict__ Bt, long ldb, int K, f32x4 (&acc)[8][4], char* lds) {
;     ...
;     for (int kt = 0; kt < nk; ++kt) {
;         char* cur = lds + (kt & 1) * 24576;
;         if (kt + 1 < nk) gemm2_stage(A, lda, Bt, ldb, kt + 1, lds + ((kt + 1) & 1) * 24576, tid);
;         bf16x8 bfr[4];
; #pragma unroll
;         for (int n = 0; n < 4; ++n) { const int row = wc * 64 + n * 16 + fr; bfr[n] = *reinterpret_cast<const bf16x8*>(cur + 16384 + row * 64 + ((fq ^ ((row >> 2) & 3)) << 4)); }
;         bf16x8 af[8];
; #pragma unroll
;         for (int m = 0; m < 8; ++m) { const int row = wr * 128 + m * 16 + fr; af[m] = *reinterpret_cast<const bf16x8*>(cur + row * 64 + ((fq ^ ((row >> 2) & 3)) << 4)); }
;         __builtin_amdgcn_s_setprio(1);
; #pragma unroll
;         for (int m = 0; m < 8; ++m)
; #pragma unroll
;             for (int n = 0; n < 4; ++n) acc[m][n] = mfma16(bfr[n], af[m], acc[m][n]);
;         __builtin_amdgcn_s_setprio(0);
;         asm volatile("s_waitcnt vmcnt(0)" ::: "memory");
;         __syncthreads();
;     }
	v_mfma_f32_16x16x32_bf16 v[86:89], v[150:153], v[210:213], v[86:89]
	v_mfma_f32_16x16x32_bf16 v[82:85], v[154:157], v[210:213], v[82:85]
	v_mfma_f32_16x16x32_bf16 v[18:21], v[158:161], v[210:213], v[18:21]
	s_add_i32 m0, s39, 0xb000
	s_add_u32 s26, s34, 0x84000
	s_addc_u32 s27, s35, 0
	global_load_lds_dwordx4 v230, s[26:27]
	v_mfma_f32_16x16x32_bf16 v[78:81], v[146:149], v[214:217], v[78:81]
	v_mfma_f32_16x16x32_bf16 v[74:77], v[150:153], v[214:217], v[74:77]
	v_mfma_f32_16x16x32_bf16 v[70:73], v[154:157], v[214:217], v[70:73]
	v_mfma_f32_16x16x32_bf16 v[14:17], v[158:161], v[214:217], v[14:17]
	v_mfma_f32_16x16x32_bf16 v[66:69], v[146:149], v[218:221], v[66:69]
	v_mfma_f32_16x16x32_bf16 v[62:65], v[150:153], v[218:221], v[62:65]
	v_mfma_f32_16x16x32_bf16 v[58:61], v[154:157], v[218:221], v[58:61]
	v_mfma_f32_16x16x32_bf16 v[10:13], v[158:161], v[218:221], v[10:13]
	v_mfma_f32_16x16x32_bf16 v[50:53], v[146:149], v[222:225], v[50:53]
	v_mfma_f32_16x16x32_bf16 v[46:49], v[150:153], v[222:225], v[46:49]
	v_mfma_f32_16x16x32_bf16 v[42:45], v[154:157], v[222:225], v[42:45]
	v_mfma_f32_16x16x32_bf16 v[6:9], v[158:161], v[222:225], v[6:9]
	v_mfma_f32_16x16x32_bf16 v[38:41], v[146:149], v[226:229], v[38:41]
	v_mfma_f32_16x16x32_bf16 v[34:37], v[150:153], v[226:229], v[34:37]
	v_mfma_f32_16x16x32_bf16 v[26:29], v[154:157], v[226:229], v[26:29]
	v_mfma_f32_16x16x32_bf16 v[2:5], v[158:161], v[226:229], v[2:5]
	s_setprio 0
	s_add_i32 s38, s38, 1
	s_cmp_lt_u32 s38, 43
	s_cbranch_scc1 .Lmy_down_loop
	s_waitcnt vmcnt(0)
	s_barrier
	ds_read_b128 v[130:133], v233
	ds_read_b128 v[134:137], v233 offset:2048
	ds_read_b128 v[138:141], v233 offset:4096
	ds_read_b128 v[142:145], v233 offset:6144
	ds_read_b128 v[146:149], v234
	ds_read_b128 v[150:153], v234 offset:2048
	ds_read_b128 v[154:157], v234 offset:4096
	ds_read_b128 v[158:161], v234 offset:6144
	ds_read_b128 v[162:165], v231
	ds_read_b128 v[166:169], v231 offset:2048
	ds_read_b128 v[170:173], v231 offset:4096
	ds_read_b128 v[174:177], v231 offset:6144
	ds_read_b128 v[182:185], v231 offset:8192
	ds_read_b128 v[186:189], v231 offset:10240
	ds_read_b128 v[190:193], v231 offset:12288
	ds_read_b128 v[194:197], v231 offset:14336
	ds_read_b128 v[198:201], v232
	ds_read_b128 v[202:205], v232 offset:2048
	ds_read_b128 v[206:209], v232 offset:4096
	ds_read_b128 v[210:213], v232 offset:6144
	ds_read_b128 v[214:217], v232 offset:8192
	ds_read_b128 v[218:221], v232 offset:10240
	ds_read_b128 v[222:225], v232 offset:12288
	ds_read_b128 v[226:229], v232 offset:14336
	s_waitcnt lgkmcnt(0)
	s_setprio 1
	v_mfma_f32_16x16x32_bf16 v[126:129], v[130:133], v[162:165], v[126:129]
	v_mfma_f32_16x16x32_bf16 v[122:125], v[134:137], v[162:165], v[122:125]
	v_mfma_f32_16x16x32_bf16 v[118:121], v[138:141], v[162:165], v[118:121]
	v_mfma_f32_16x16x32_bf16 v[54:57], v[142:145], v[162:165], v[54:57]
	v_mfma_f32_16x16x32_bf16 v[114:117], v[130:133], v[166:169], v[114:117]
	v_mfma_f32_16x16x32_bf16 v[110:113], v[134:137], v[166:169], v[110:113]
	v_mfma_f32_16x16x32_bf16 v[106:109], v[138:141], v[166:169], v[106:109]
	v_mfma_f32_16x16x32_bf16 v[30:33], v[142:145], v[166:169], v[30:33]
	v_mfma_f32_16x16x32_bf16 v[102:105], v[130:133], v[170:173], v[102:105]
	v_mfma_f32_16x16x32_bf16 v[98:101], v[134:137], v[170:173], v[98:101]
	v_mfma_f32_16x16x32_bf16 v[94:97], v[138:141], v[170:173], v[94:97]
	v_mfma_f32_16x16x32_bf16 v[22:25], v[142:145], v[170:173], v[22:25]
	v_mfma_f32_16x16x32_bf16 v[90:93], v[130:133], v[174:177], v[90:93]
	v_mfma_f32_16x16x32_bf16 v[86:89], v[134:137], v[174:177], v[86:89]
	v_mfma_f32_16x16x32_bf16 v[82:85], v[138:141], v[174:177], v[82:85]
	v_mfma_f32_16x16x32_bf16 v[18:21], v[142:145], v[174:177], v[18:21]
	v_mfma_f32_16x16x32_bf16 v[78:81], v[130:133], v[182:185], v[78:81]
	v_mfma_f32_16x16x32_bf16 v[74:77], v[134:137], v[182:185], v[74:77]
	v_mfma_f32_16x16x32_bf16 v[70:73], v[138:141], v[182:185], v[70:73]
	v_mfma_f32_16x16x32_bf16 v[14:17], v[142:145], v[182:185], v[14:17]
	v_mfma_f32_16x16x32_bf16 v[66:69], v[130:133], v[186:189], v[66:69]
	v_mfma_f32_16x16x32_bf16 v[62:65], v[134:137], v[186:189], v[62:65]
	v_mfma_f32_16x16x32_bf16 v[58:61], v[138:141], v[186:189], v[58:61]
	v_mfma_f32_16x16x32_bf16 v[10:13], v[142:145], v[186:189], v[10:13]
	v_mfma_f32_16x16x32_bf16 v[50:53], v[130:133], v[190:193], v[50:53]
	v_mfma_f32_16x16x32_bf16 v[46:49], v[134:137], v[190:193], v[46:49]
	v_mfma_f32_16x16x32_bf16 v[42:45], v[138:141], v[190:193], v[42:45]
	v_mfma_f32_16x16x32_bf16 v[6:9], v[142:145], v[190:193], v[6:9]
	v_mfma_f32_16x16x32_bf16 v[38:41], v[130:133], v[194:197], v[38:41]
	v_mfma_f32_16x16x32_bf16 v[34:37], v[134:137], v[194:197], v[34:37]
	v_mfma_f32_16x16x32_bf16 v[26:29], v[138:141], v[194:197], v[26:29]
	v_mfma_f32_16x16x32_bf16 v[2:5], v[142:145], v[194:197], v[2:5]
	v_mfma_f32_16x16x32_bf16 v[126:129], v[146:149], v[198:201], v[126:129]
	v_mfma_f32_16x16x32_bf16 v[122:125], v[150:153], v[198:201], v[122:125]
	v_mfma_f32_16x16x32_bf16 v[118:121], v[154:157], v[198:201], v[118:121]
	v_mfma_f32_16x16x32_bf16 v[54:57], v[158:161], v[198:201], v[54:57]
	v_mfma_f32_16x16x32_bf16 v[114:117], v[146:149], v[202:205], v[114:117]
	v_mfma_f32_16x16x32_bf16 v[110:113], v[150:153], v[202:205], v[110:113]
	v_mfma_f32_16x16x32_bf16 v[106:109], v[154:157], v[202:205], v[106:109]
	v_mfma_f32_16x16x32_bf16 v[30:33], v[158:161], v[202:205], v[30:33]
	v_mfma_f32_16x16x32_bf16 v[102:105], v[146:149], v[206:209], v[102:105]
	v_mfma_f32_16x16x32_bf16 v[98:101], v[150:153], v[206:209], v[98:101]
	v_mfma_f32_16x16x32_bf16 v[94:97], v[154:157], v[206:209], v[94:97]
	v_mfma_f32_16x16x32_bf16 v[22:25], v[158:161], v[206:209], v[22:25]
; __device__ __forceinline__ int tid_() { int x = threadIdx.x; asm volatile("" : "+v"(x)); return x; }
; __device__ __forceinline__ void resid_tile2(const f32x4 (&acc)[8][4], float* __restrict__ h, int row0, int col0, const float* __restrict__ gate) {
;     const int tid = tid_(), wid = tid >> 6, lane = tid & 63, wr = wid >> 1, wc = wid & 1, fr = lane & 15, fq = lane >> 4;
;     const int b = row0 >> 11;
; #pragma unroll
;     for (int n = 0; n < 4; ++n) {
;         const int col = col0 + wc * 64 + n * 16 + fq * 4;
;         const f32x4 gv = *(const f32x4*)(gate + (size_t)b * 6144 + col);
; #pragma unroll
;         for (int m = 0; m < 8; ++m) {
;             float* hp = h + (size_t)(row0 + wr * 128 + m * 16 + fr) * DM + col;
;             const f32x4 o = *(const f32x4*)hp + gv * acc[m][n];
;             *(f32x4*)hp = o;
;         }
;     }
; }
; __device__ void ph_gemm_down(const Params& P, int l, char* lds) {
;     ...
;         resid_tile2(acc, P.out, mt * 256, nt * 128, gate);
	v_mfma_f32_16x16x32_bf16 v[90:93], v[146:149], v[210:213], v[90:93]
	v_mfma_f32_16x16x32_bf16 v[86:89], v[150:153], v[210:213], v[86:89]
	v_mfma_f32_16x16x32_bf16 v[82:85], v[154:157], v[210:213], v[82:85]
	v_mfma_f32_16x16x32_bf16 v[18:21], v[158:161], v[210:213], v[18:21]
	v_mfma_f32_16x16x32_bf16 v[78:81], v[146:149], v[214:217], v[78:81]
	v_mfma_f32_16x16x32_bf16 v[74:77], v[150:153], v[214:217], v[74:77]
	v_mfma_f32_16x16x32_bf16 v[70:73], v[154:157], v[214:217], v[70:73]
	v_mfma_f32_16x16x32_bf16 v[14:17], v[158:161], v[214:217], v[14:17]
	v_mfma_f32_16x16x32_bf16 v[66:69], v[146:149], v[218:221], v[66:69]
	v_mfma_f32_16x16x32_bf16 v[62:65], v[150:153], v[218:221], v[62:65]
	v_mfma_f32_16x16x32_bf16 v[58:61], v[154:157], v[218:221], v[58:61]
	v_mfma_f32_16x16x32_bf16 v[10:13], v[158:161], v[218:221], v[10:13]
	v_mfma_f32_16x16x32_bf16 v[50:53], v[146:149], v[222:225], v[50:53]
	v_mfma_f32_16x16x32_bf16 v[46:49], v[150:153], v[222:225], v[46:49]
	v_mfma_f32_16x16x32_bf16 v[42:45], v[154:157], v[222:225], v[42:45]
	v_mfma_f32_16x16x32_bf16 v[6:9], v[158:161], v[222:225], v[6:9]
	v_mfma_f32_16x16x32_bf16 v[38:41], v[146:149], v[226:229], v[38:41]
	v_mfma_f32_16x16x32_bf16 v[34:37], v[150:153], v[226:229], v[34:37]
	v_mfma_f32_16x16x32_bf16 v[26:29], v[154:157], v[226:229], v[26:29]
	v_mfma_f32_16x16x32_bf16 v[2:5], v[158:161], v[226:229], v[2:5]
	s_setprio 0
	v_mov_b32_e32 v182, 0x2c60000
	v_mov_b32_e32 v183, 0x540
	v_mov_b32_e32 v184, 0x6000
	v_mov_b32_e32 v185, 0x2000
	v_mov_b32_e32 v186, 0x160000
	v_mov_b32_e32 v187, 0x70
	v_mov_b32_e32 v188, 0x1100
	v_mov_b32_e32 v218, 0
	v_mov_b32_e32 v219, 0
	v_mov_b32_e32 v220, 0
	v_mov_b32_e32 v221, 0
	s_nop 7
	s_nop 7
	v_mov_b32_e32 v146, v102
	v_mov_b32_e32 v147, v103
	v_mov_b32_e32 v148, v104
	v_mov_b32_e32 v149, v105
	v_mov_b32_e32 v150, v78
	v_mov_b32_e32 v151, v79
	v_mov_b32_e32 v152, v80
	v_mov_b32_e32 v153, v81
	v_mov_b32_e32 v154, v66
	v_mov_b32_e32 v155, v67
	v_mov_b32_e32 v156, v68
	v_mov_b32_e32 v157, v69
	v_mov_b32_e32 v158, v50
	v_mov_b32_e32 v159, v51
	v_mov_b32_e32 v160, v52
	v_mov_b32_e32 v161, v53
	v_mov_b32_e32 v0, v178
	s_waitcnt vmcnt(0)
	s_barrier
	s_lshl_b32 s0, s30, 7
	v_lshrrev_b32_e32 v51, 2, v0
	v_and_b32_e32 v50, 64, v0
	v_and_b32_e32 v51, 12, v51
	v_or3_b32 v50, v50, s0, v51
	v_and_b32_e32 v51, 0xffffff80, v0
	s_ashr_i32 s1, s29, 3
	v_lshl_add_u32 v51, s29, 8, v51
	s_mul_hi_i32 s26, s1, 0x6000
	s_mulk_i32 s1, 0x6000
	v_and_or_b32 v104, v0, 15, v51
	v_ashrrev_i32_e32 v51, 31, v50
	v_readlane_b32 s48, v241, 13
	s_add_u32 s0, s24, s1
	v_ashrrev_i32_e32 v105, 31, v104
	v_lshlrev_b64 v[50:51], 2, v[50:51]
	v_readlane_b32 s50, v241, 15
	v_readlane_b32 s51, v241, 16
	s_addc_u32 s1, s28, s26
	v_lshlrev_b64 v[52:53], 12, v[104:105]
	v_lshl_add_u64 v[134:135], s[50:51], 0, v[50:51]
	v_lshl_add_u64 v[102:103], s[0:1], 0, v[50:51]
	v_lshl_add_u64 v[68:69], v[134:135], 0, v[52:53]
	global_load_dwordx4 v[130:133], v[102:103], off
	global_load_dwordx4 v[50:53], v[68:69], off
	v_readlane_b32 s0, v239, 10
	s_add_i32 s21, s21, s0
	s_cmpk_gt_i32 s21, 0x3ff
	v_readlane_b32 s49, v241, 14
	v_readlane_b32 s1, v239, 11
	s_waitcnt vmcnt(0)
	v_pk_fma_f32 v[52:53], v[128:129], v[132:133], v[52:53]
	v_pk_fma_f32 v[50:51], v[126:127], v[130:131], v[50:51]
	global_store_dwordx4 v[68:69], v[50:53], off
	s_nop 1
	v_or_b32_e32 v50, 16, v104
	v_ashrrev_i32_e32 v51, 31, v50
	v_lshlrev_b64 v[50:51], 12, v[50:51]
	v_lshl_add_u64 v[52:53], v[134:135], 0, v[50:51]
	global_load_dwordx4 v[78:81], v[52:53], off
	v_or_b32_e32 v50, 32, v104
	v_ashrrev_i32_e32 v51, 31, v50
	v_lshlrev_b64 v[50:51], 12, v[50:51]
	v_lshl_add_u64 v[66:67], v[134:135], 0, v[50:51]
	v_or_b32_e32 v50, 48, v104
	v_ashrrev_i32_e32 v51, 31, v50
	v_lshlrev_b64 v[50:51], 12, v[50:51]
	s_waitcnt vmcnt(0)
	v_pk_fma_f32 v[80:81], v[116:117], v[132:133], v[80:81]
	v_pk_fma_f32 v[78:79], v[114:115], v[130:131], v[78:79]
	global_store_dwordx4 v[52:53], v[78:81], off
	global_load_dwordx4 v[78:81], v[66:67], off
	s_waitcnt vmcnt(0)
	v_pk_fma_f32 v[80:81], v[148:149], v[132:133], v[80:81]
	v_pk_fma_f32 v[78:79], v[146:147], v[130:131], v[78:79]
	global_store_dwordx4 v[66:67], v[78:81], off
	s_nop 1
	v_lshl_add_u64 v[78:79], v[134:135], 0, v[50:51]
	global_load_dwordx4 v[114:117], v[78:79], off
	v_or_b32_e32 v50, 64, v104
	v_ashrrev_i32_e32 v51, 31, v50
	v_lshlrev_b64 v[50:51], 12, v[50:51]
	v_lshl_add_u64 v[80:81], v[134:135], 0, v[50:51]
	v_or_b32_e32 v50, 0x50, v104
	v_ashrrev_i32_e32 v51, 31, v50
	v_lshlrev_b64 v[50:51], 12, v[50:51]
	s_waitcnt vmcnt(0)
	v_pk_fma_f32 v[92:93], v[92:93], v[132:133], v[116:117]
	v_pk_fma_f32 v[90:91], v[90:91], v[130:131], v[114:115]
	global_store_dwordx4 v[78:79], v[90:93], off
	global_load_dwordx4 v[90:93], v[80:81], off
	s_waitcnt vmcnt(0)
	v_pk_fma_f32 v[92:93], v[152:153], v[132:133], v[92:93]
	v_pk_fma_f32 v[90:91], v[150:151], v[130:131], v[90:91]
	global_store_dwordx4 v[80:81], v[90:93], off
	s_nop 1
	v_lshl_add_u64 v[90:91], v[134:135], 0, v[50:51]
	global_load_dwordx4 v[114:117], v[90:91], off
	v_or_b32_e32 v50, 0x60, v104
	v_ashrrev_i32_e32 v51, 31, v50
	v_lshlrev_b64 v[50:51], 12, v[50:51]
	v_lshl_add_u64 v[92:93], v[134:135], 0, v[50:51]
	v_or_b32_e32 v50, 0x70, v104
	v_ashrrev_i32_e32 v51, 31, v50
	v_lshlrev_b64 v[50:51], 12, v[50:51]
	v_lshl_add_u64 v[50:51], v[134:135], 0, v[50:51]
	s_waitcnt vmcnt(0)
	v_pk_fma_f32 v[116:117], v[156:157], v[132:133], v[116:117]
	v_pk_fma_f32 v[114:115], v[154:155], v[130:131], v[114:115]
	global_store_dwordx4 v[90:91], v[114:117], off
	global_load_dwordx4 v[114:117], v[92:93], off
	s_waitcnt vmcnt(0)
; __device__ __forceinline__ int tid_() { int x = threadIdx.x; asm volatile("" : "+v"(x)); return x; }
; __device__ __forceinline__ void resid_tile2(const f32x4 (&acc)[8][4], float* __restrict__ h, int row0, int col0, const float* __restrict__ gate) {
;     const int tid = tid_(), wid = tid >> 6, lane = tid & 63, wr = wid >> 1, wc = wid & 1, fr = lane & 15, fq = lane >> 4;
;     const int b = row0 >> 11;
; #pragma unroll
;     for (int n = 0; n < 4; ++n) {
;         const int col = col0 + wc * 64 + n * 16 + fq * 4;
;         const f32x4 gv = *(const f32x4*)(gate + (size_t)b * 6144 + col);
; #pragma unroll
;         for (int m = 0; m < 8; ++m) {
;             float* hp = h + (size_t)(row0 + wr * 128 + m * 16 + fr) * DM + col;
;             const f32x4 o = *(const f32x4*)hp + gv * acc[m][n];
;             *(f32x4*)hp = o;
;         }
;     }
; }
	v_pk_fma_f32 v[116:117], v[160:161], v[132:133], v[116:117]
	v_pk_fma_f32 v[114:115], v[158:159], v[130:131], v[114:115]
	global_store_dwordx4 v[92:93], v[114:117], off
	global_load_dwordx4 v[114:117], v[50:51], off
	s_waitcnt vmcnt(0)
	v_pk_fma_f32 v[40:41], v[40:41], v[132:133], v[116:117]
	v_pk_fma_f32 v[38:39], v[38:39], v[130:131], v[114:115]
	global_store_dwordx4 v[50:51], v[38:41], off
	global_load_dwordx4 v[38:41], v[102:103], off offset:64
	s_nop 0
	global_load_dwordx4 v[114:117], v[68:69], off offset:64
	s_waitcnt vmcnt(0)
	v_pk_fma_f32 v[116:117], v[124:125], v[40:41], v[116:117]
	v_pk_fma_f32 v[114:115], v[122:123], v[38:39], v[114:115]
	global_store_dwordx4 v[68:69], v[114:117], off offset:64
	global_load_dwordx4 v[114:117], v[52:53], off offset:64
	s_waitcnt vmcnt(0)
	v_pk_fma_f32 v[112:113], v[112:113], v[40:41], v[116:117]
	v_pk_fma_f32 v[110:111], v[110:111], v[38:39], v[114:115]
	global_store_dwordx4 v[52:53], v[110:113], off offset:64
	global_load_dwordx4 v[110:113], v[66:67], off offset:64
	s_waitcnt vmcnt(0)
	v_pk_fma_f32 v[100:101], v[100:101], v[40:41], v[112:113]
	v_pk_fma_f32 v[98:99], v[98:99], v[38:39], v[110:111]
	global_store_dwordx4 v[66:67], v[98:101], off offset:64
	global_load_dwordx4 v[98:101], v[78:79], off offset:64
	s_waitcnt vmcnt(0)
	v_pk_fma_f32 v[88:89], v[88:89], v[40:41], v[100:101]
	v_pk_fma_f32 v[86:87], v[86:87], v[38:39], v[98:99]
	global_store_dwordx4 v[78:79], v[86:89], off offset:64
	global_load_dwordx4 v[86:89], v[80:81], off offset:64
	s_waitcnt vmcnt(0)
	v_pk_fma_f32 v[76:77], v[76:77], v[40:41], v[88:89]
	v_pk_fma_f32 v[74:75], v[74:75], v[38:39], v[86:87]
	global_store_dwordx4 v[80:81], v[74:77], off offset:64
	global_load_dwordx4 v[74:77], v[90:91], off offset:64
	s_waitcnt vmcnt(0)
	v_pk_fma_f32 v[64:65], v[64:65], v[40:41], v[76:77]
	v_pk_fma_f32 v[62:63], v[62:63], v[38:39], v[74:75]
	global_store_dwordx4 v[90:91], v[62:65], off offset:64
	global_load_dwordx4 v[62:65], v[92:93], off offset:64
	s_waitcnt vmcnt(0)
	v_pk_fma_f32 v[48:49], v[48:49], v[40:41], v[64:65]
	v_pk_fma_f32 v[46:47], v[46:47], v[38:39], v[62:63]
	global_store_dwordx4 v[92:93], v[46:49], off offset:64
	global_load_dwordx4 v[46:49], v[50:51], off offset:64
	s_waitcnt vmcnt(0)
	v_pk_fma_f32 v[36:37], v[36:37], v[40:41], v[48:49]
	v_pk_fma_f32 v[34:35], v[34:35], v[38:39], v[46:47]
	global_store_dwordx4 v[50:51], v[34:37], off offset:64
	global_load_dwordx4 v[34:37], v[102:103], off offset:128
	s_nop 0
	global_load_dwordx4 v[38:41], v[68:69], off offset:128
	s_waitcnt vmcnt(0)
	v_pk_fma_f32 v[40:41], v[120:121], v[36:37], v[40:41]
	v_pk_fma_f32 v[38:39], v[118:119], v[34:35], v[38:39]
	global_store_dwordx4 v[68:69], v[38:41], off offset:128
	global_load_dwordx4 v[38:41], v[52:53], off offset:128
	s_waitcnt vmcnt(0)
	v_pk_fma_f32 v[40:41], v[108:109], v[36:37], v[40:41]
	v_pk_fma_f32 v[38:39], v[106:107], v[34:35], v[38:39]
	global_store_dwordx4 v[52:53], v[38:41], off offset:128
	global_load_dwordx4 v[38:41], v[66:67], off offset:128
	s_waitcnt vmcnt(0)
	v_pk_fma_f32 v[40:41], v[96:97], v[36:37], v[40:41]
	v_pk_fma_f32 v[38:39], v[94:95], v[34:35], v[38:39]
	global_store_dwordx4 v[66:67], v[38:41], off offset:128
	global_load_dwordx4 v[38:41], v[78:79], off offset:128
	s_waitcnt vmcnt(0)
	v_pk_fma_f32 v[40:41], v[84:85], v[36:37], v[40:41]
	v_pk_fma_f32 v[38:39], v[82:83], v[34:35], v[38:39]
	global_store_dwordx4 v[78:79], v[38:41], off offset:128
	global_load_dwordx4 v[38:41], v[80:81], off offset:128
	s_waitcnt vmcnt(0)
	v_pk_fma_f32 v[40:41], v[72:73], v[36:37], v[40:41]
	v_pk_fma_f32 v[38:39], v[70:71], v[34:35], v[38:39]
	global_store_dwordx4 v[80:81], v[38:41], off offset:128
	global_load_dwordx4 v[38:41], v[90:91], off offset:128
	s_waitcnt vmcnt(0)
	v_pk_fma_f32 v[40:41], v[60:61], v[36:37], v[40:41]
	v_pk_fma_f32 v[38:39], v[58:59], v[34:35], v[38:39]
	global_store_dwordx4 v[90:91], v[38:41], off offset:128
	global_load_dwordx4 v[38:41], v[92:93], off offset:128
	s_waitcnt vmcnt(0)
	v_pk_fma_f32 v[40:41], v[44:45], v[36:37], v[40:41]
	v_pk_fma_f32 v[38:39], v[42:43], v[34:35], v[38:39]
	global_store_dwordx4 v[92:93], v[38:41], off offset:128
	global_load_dwordx4 v[38:41], v[50:51], off offset:128
	s_waitcnt vmcnt(0)
	v_pk_fma_f32 v[28:29], v[28:29], v[36:37], v[40:41]
	v_pk_fma_f32 v[26:27], v[26:27], v[34:35], v[38:39]
	global_store_dwordx4 v[50:51], v[26:29], off offset:128
	global_load_dwordx4 v[26:29], v[102:103], off offset:192
	s_nop 0
	global_load_dwordx4 v[34:37], v[68:69], off offset:192
	s_waitcnt vmcnt(0)
	v_pk_fma_f32 v[36:37], v[56:57], v[28:29], v[36:37]
	v_pk_fma_f32 v[34:35], v[54:55], v[26:27], v[34:35]
	global_store_dwordx4 v[68:69], v[34:37], off offset:192
	global_load_dwordx4 v[34:37], v[52:53], off offset:192
	s_waitcnt vmcnt(0)
	v_pk_fma_f32 v[32:33], v[32:33], v[28:29], v[36:37]
	v_pk_fma_f32 v[30:31], v[30:31], v[26:27], v[34:35]
	global_store_dwordx4 v[52:53], v[30:33], off offset:192
	global_load_dwordx4 v[30:33], v[66:67], off offset:192
	s_waitcnt vmcnt(0)
	v_pk_fma_f32 v[24:25], v[24:25], v[28:29], v[32:33]
	v_pk_fma_f32 v[22:23], v[22:23], v[26:27], v[30:31]
	global_store_dwordx4 v[66:67], v[22:25], off offset:192
	global_load_dwordx4 v[22:25], v[78:79], off offset:192
	s_waitcnt vmcnt(0)
	v_pk_fma_f32 v[20:21], v[20:21], v[28:29], v[24:25]
	v_pk_fma_f32 v[18:19], v[18:19], v[26:27], v[22:23]
	global_store_dwordx4 v[78:79], v[18:21], off offset:192
	global_load_dwordx4 v[18:21], v[80:81], off offset:192
	s_waitcnt vmcnt(0)
	v_pk_fma_f32 v[16:17], v[16:17], v[28:29], v[20:21]
	v_pk_fma_f32 v[14:15], v[14:15], v[26:27], v[18:19]
	global_store_dwordx4 v[80:81], v[14:17], off offset:192
	global_load_dwordx4 v[14:17], v[90:91], off offset:192
	s_waitcnt vmcnt(0)
	v_pk_fma_f32 v[12:13], v[12:13], v[28:29], v[16:17]
	v_pk_fma_f32 v[10:11], v[10:11], v[26:27], v[14:15]
	global_store_dwordx4 v[90:91], v[10:13], off offset:192
	global_load_dwordx4 v[10:13], v[92:93], off offset:192
	s_waitcnt vmcnt(0)
	v_pk_fma_f32 v[8:9], v[8:9], v[28:29], v[12:13]
	v_pk_fma_f32 v[6:7], v[6:7], v[26:27], v[10:11]
	global_store_dwordx4 v[92:93], v[6:9], off offset:192
	global_load_dwordx4 v[6:9], v[50:51], off offset:192
	s_waitcnt vmcnt(0)
	v_pk_fma_f32 v[4:5], v[4:5], v[28:29], v[8:9]
	v_pk_fma_f32 v[2:3], v[2:3], v[26:27], v[6:7]
	global_store_dwordx4 v[50:51], v[2:5], off offset:192
	s_cbranch_scc0 .LBB0_375

; __device__ __forceinline__ int tid_() { int x = threadIdx.x; asm volatile("" : "+v"(x)); return x; }
; __device__ __forceinline__ void gemm2_stage(const bf16_t* __restrict__ A, long lda, const bf16_t* __restrict__ Bt, long ldb, int kt, char* buf, int tid) {
; #pragma unroll
;     for (int i = 0; i < 4; ++i) {
;         const int b = tid * 16 + i * 4096, r = b >> 6, c = ((b & 63) >> 4) ^ ((r >> 2) & 3);
;         __builtin_amdgcn_global_load_lds((const unsigned*)(A + (long)r * lda + kt * 32 + c * 8), (__attribute__((address_space(3))) unsigned*)(buf + b), 16, 0, 0);
;     }
; #pragma unroll
;     for (int i = 0; i < 2; ++i) {
;         const int b = tid * 16 + i * 4096, r = b >> 6, c = ((b & 63) >> 4) ^ ((r >> 2) & 3);
;         __builtin_amdgcn_global_load_lds((const unsigned*)(Bt + (long)r * ldb + kt * 32 + c * 8), (__attribute__((address_space(3))) unsigned*)(buf + 16384 + b), 16, 0, 0);
;     }
; }
; __device__ __forceinline__ void gemm_acc2(const bf16_t* __restrict__ A, long lda, const bf16_t* __restrict__ Bt, long ldb, int K, f32x4 (&acc)[8][4], char* lds) {
;     const int tid = tid_(), wid = tid >> 6, lane = tid & 63, wr = wid >> 1, wc = wid & 1, fr = lane & 15, fq = lane >> 4;
;     const int nk = K >> 5;
;     gemm2_stage(A, lda, Bt, ldb, 0, lds, tid);
;     asm volatile("s_waitcnt vmcnt(0)" ::: "memory");
;     __syncthreads();
; __device__ void ph_gemm_p(const Params& P, char* lds) {
;     ...
;         const int mt = item / 55, nt = item % 55;
;         f32x4 acc[8][4]; zero_acc2(acc);
;         gemm_acc2(U + (size_t)mt * 256 * DM, DM, Wt + (size_t)nt * 128 * DM, DM, DM, acc, lds);
.Lmy_p_noperm:
	s_mul_hi_u32 s0, s38, 0x94f20a
	s_mul_i32 s1, s0, 0x1b8
	s_sub_i32 s1, s38, s1
	s_lshr_b32 s38, s1, 3
	s_and_b32 s1, s1, 7
	s_lshl_b32 s0, s0, 3
	s_add_i32 s0, s0, s1
	s_mov_b32 s1, 0
	v_lshlrev_b32_e32 v235, 4, v178
	v_lshrrev_b32_e32 v236, 3, v178
	v_and_b32_e32 v237, 7, v178
	v_and_b32_e32 v232, 7, v236
	v_xor_b32_e32 v237, v237, v232
	v_lshlrev_b32_e32 v237, 4, v237
	s_movk_i32 s26, 0x800
	v_mad_u32_u24 v230, v236, s26, v237
	v_and_b32_e32 v236, 15, v178
	v_bfe_u32 v237, v178, 4, 2
	v_and_b32_e32 v232, 7, v236
	v_xor_b32_e32 v237, v237, v232
	v_lshlrev_b32_e32 v237, 4, v237
	v_lshl_or_b32 v237, v236, 7, v237
	v_bfe_u32 v236, v178, 7, 1
	v_lshl_add_u32 v231, v236, 14, v237
	v_bfe_u32 v236, v178, 6, 1
	v_lshl_add_u32 v233, v236, 13, v237
	v_add_u32_e32 v233, 0x8000, v233
	v_xor_b32_e32 v234, 64, v233
	v_xor_b32_e32 v232, 64, v231
	v_readlane_b32 s42, v241, 31
	v_readlane_b32 s43, v241, 32
	s_lshl_b32 s26, s0, 19
	s_add_u32 s42, s42, s26
	s_addc_u32 s43, s43, 0
	s_lshl_b32 s26, s38, 18
	s_add_u32 s44, s74, s26
	s_addc_u32 s45, s75, 0
	v_readfirstlane_b32 s28, v235
	s_nop 0
	s_add_i32 m0, s28, 0x0
	s_add_u32 s26, s42, 0x0
	s_addc_u32 s27, s43, 0
	global_load_lds_dwordx4 v230, s[26:27]
	s_add_i32 m0, s28, 0x1000
	s_add_u32 s26, s42, 0x10000
	s_addc_u32 s27, s43, 0
	global_load_lds_dwordx4 v230, s[26:27]
	s_add_i32 m0, s28, 0x2000
	s_add_u32 s26, s42, 0x20000
	s_addc_u32 s27, s43, 0
	global_load_lds_dwordx4 v230, s[26:27]
	s_add_i32 m0, s28, 0x3000
	s_add_u32 s26, s42, 0x30000
	s_addc_u32 s27, s43, 0
	global_load_lds_dwordx4 v230, s[26:27]
	s_add_i32 m0, s28, 0x4000
	s_add_u32 s26, s42, 0x40000
	s_addc_u32 s27, s43, 0
	global_load_lds_dwordx4 v230, s[26:27]
	s_add_i32 m0, s28, 0x5000
	s_add_u32 s26, s42, 0x50000
	s_addc_u32 s27, s43, 0
	global_load_lds_dwordx4 v230, s[26:27]
	s_add_i32 m0, s28, 0x6000
	s_add_u32 s26, s42, 0x60000
	s_addc_u32 s27, s43, 0
	global_load_lds_dwordx4 v230, s[26:27]
	s_add_i32 m0, s28, 0x7000
	s_add_u32 s26, s42, 0x70000
	s_addc_u32 s27, s43, 0
	global_load_lds_dwordx4 v230, s[26:27]
	s_add_i32 m0, s28, 0x8000
	s_add_u32 s26, s44, 0x0
	s_addc_u32 s27, s45, 0
	global_load_lds_dwordx4 v230, s[26:27]
	s_add_i32 m0, s28, 0x9000
	s_add_u32 s26, s44, 0x10000
	s_addc_u32 s27, s45, 0
	global_load_lds_dwordx4 v230, s[26:27]
	s_add_i32 m0, s28, 0xa000
	s_add_u32 s26, s44, 0x20000
	s_addc_u32 s27, s45, 0
	global_load_lds_dwordx4 v230, s[26:27]
	s_add_i32 m0, s28, 0xb000
	s_add_u32 s26, s44, 0x30000
	s_addc_u32 s27, s45, 0
	global_load_lds_dwordx4 v230, s[26:27]
	s_waitcnt vmcnt(12)
	v_mov_b32_e32 v2, 0
	v_mov_b32_e32 v3, 0
	v_mov_b32_e32 v4, 0
	v_mov_b32_e32 v5, 0
	v_mov_b32_e32 v6, 0
	v_mov_b32_e32 v7, 0
	v_mov_b32_e32 v8, 0
	v_mov_b32_e32 v9, 0
	v_mov_b32_e32 v10, 0
	v_mov_b32_e32 v11, 0
	v_mov_b32_e32 v12, 0
	v_mov_b32_e32 v13, 0
	v_mov_b32_e32 v14, 0
	v_mov_b32_e32 v15, 0
	v_mov_b32_e32 v16, 0
	v_mov_b32_e32 v17, 0
	v_mov_b32_e32 v18, 0
	v_mov_b32_e32 v19, 0
	v_mov_b32_e32 v20, 0
	v_mov_b32_e32 v21, 0
	v_mov_b32_e32 v22, 0
	v_mov_b32_e32 v23, 0
	v_mov_b32_e32 v24, 0
	v_mov_b32_e32 v25, 0
	v_mov_b32_e32 v26, 0
	v_mov_b32_e32 v27, 0
	v_mov_b32_e32 v28, 0
	v_mov_b32_e32 v29, 0
	v_mov_b32_e32 v30, 0
	v_mov_b32_e32 v31, 0
	v_mov_b32_e32 v32, 0
	v_mov_b32_e32 v33, 0
	v_mov_b32_e32 v34, 0
	v_mov_b32_e32 v35, 0
	v_mov_b32_e32 v36, 0
	v_mov_b32_e32 v37, 0
	v_mov_b32_e32 v38, 0
	v_mov_b32_e32 v39, 0
	v_mov_b32_e32 v40, 0
	v_mov_b32_e32 v41, 0
	v_mov_b32_e32 v42, 0
	v_mov_b32_e32 v43, 0
	v_mov_b32_e32 v44, 0
	v_mov_b32_e32 v45, 0
	v_mov_b32_e32 v46, 0
	v_mov_b32_e32 v47, 0
	v_mov_b32_e32 v48, 0
	v_mov_b32_e32 v49, 0
	v_mov_b32_e32 v50, 0
	v_mov_b32_e32 v51, 0
	v_mov_b32_e32 v52, 0
	v_mov_b32_e32 v53, 0
	v_mov_b32_e32 v54, 0
	v_mov_b32_e32 v55, 0
	v_mov_b32_e32 v56, 0
	v_mov_b32_e32 v57, 0
	v_mov_b32_e32 v58, 0
	v_mov_b32_e32 v59, 0
	v_mov_b32_e32 v60, 0
	v_mov_b32_e32 v61, 0
	v_mov_b32_e32 v62, 0
	v_mov_b32_e32 v63, 0
	v_mov_b32_e32 v64, 0
	v_mov_b32_e32 v65, 0
	v_mov_b32_e32 v66, 0
	v_mov_b32_e32 v67, 0
	v_mov_b32_e32 v68, 0
	v_mov_b32_e32 v69, 0
	v_mov_b32_e32 v70, 0
	v_mov_b32_e32 v71, 0
	v_mov_b32_e32 v72, 0
	v_mov_b32_e32 v73, 0
	v_mov_b32_e32 v74, 0
	v_mov_b32_e32 v75, 0
	v_mov_b32_e32 v76, 0
	v_mov_b32_e32 v77, 0
	v_mov_b32_e32 v78, 0
	v_mov_b32_e32 v79, 0
	v_mov_b32_e32 v80, 0
	v_mov_b32_e32 v81, 0
	v_mov_b32_e32 v82, 0
	v_mov_b32_e32 v83, 0
	v_mov_b32_e32 v84, 0
	v_mov_b32_e32 v85, 0
	v_mov_b32_e32 v86, 0
	v_mov_b32_e32 v87, 0
	v_mov_b32_e32 v88, 0
	v_mov_b32_e32 v89, 0
	v_mov_b32_e32 v90, 0
	v_mov_b32_e32 v91, 0
	v_mov_b32_e32 v92, 0
	v_mov_b32_e32 v93, 0
	v_mov_b32_e32 v94, 0
	v_mov_b32_e32 v95, 0
	v_mov_b32_e32 v96, 0
	v_mov_b32_e32 v97, 0
	v_mov_b32_e32 v98, 0
	v_mov_b32_e32 v99, 0
	v_mov_b32_e32 v100, 0
	v_mov_b32_e32 v101, 0
	v_mov_b32_e32 v102, 0
	v_mov_b32_e32 v103, 0
	v_mov_b32_e32 v104, 0
	v_mov_b32_e32 v105, 0
	v_mov_b32_e32 v106, 0
	v_mov_b32_e32 v107, 0
	v_mov_b32_e32 v108, 0
	v_mov_b32_e32 v109, 0
	v_mov_b32_e32 v110, 0
	v_mov_b32_e32 v111, 0
	v_mov_b32_e32 v112, 0
	v_mov_b32_e32 v113, 0
	v_mov_b32_e32 v114, 0
	v_mov_b32_e32 v115, 0
	v_mov_b32_e32 v116, 0
	v_mov_b32_e32 v117, 0
	v_mov_b32_e32 v118, 0
	v_mov_b32_e32 v119, 0
	v_mov_b32_e32 v120, 0
	v_mov_b32_e32 v121, 0
	v_mov_b32_e32 v122, 0
	v_mov_b32_e32 v123, 0
	v_mov_b32_e32 v124, 0
	v_mov_b32_e32 v125, 0
	v_mov_b32_e32 v126, 0
	v_mov_b32_e32 v127, 0
	v_mov_b32_e32 v128, 0
	v_mov_b32_e32 v129, 0
	s_mov_b32 s24, 0
; __device__ __forceinline__ f32x4 mfma16(bf16x8 a, bf16x8 b, f32x4 c) { return __builtin_amdgcn_mfma_f32_16x16x32_bf16(a, b, c, 0, 0, 0); }
; __device__ __forceinline__ void gemm_acc2(const bf16_t* __restrict__ A, long lda, const bf16_t* __restrict__ Bt, long ldb, int K, f32x4 (&acc)[8][4], char* lds) {
;     ...
;     for (int kt = 0; kt < nk; ++kt) {
;         char* cur = lds + (kt & 1) * 24576;
;         if (kt + 1 < nk) gemm2_stage(A, lda, Bt, ldb, kt + 1, lds + ((kt + 1) & 1) * 24576, tid);
;         bf16x8 bfr[4];
; #pragma unroll
;         for (int n = 0; n < 4; ++n) { const int row = wc * 64 + n * 16 + fr; bfr[n] = *reinterpret_cast<const bf16x8*>(cur + 16384 + row * 64 + ((fq ^ ((row >> 2) & 3)) << 4)); }
;         bf16x8 af[8];
; #pragma unroll
;         for (int m = 0; m < 8; ++m) { const int row = wr * 128 + m * 16 + fr; af[m] = *reinterpret_cast<const bf16x8*>(cur + row * 64 + ((fq ^ ((row >> 2) & 3)) << 4)); }
;         __builtin_amdgcn_s_setprio(1);
; #pragma unroll
;         for (int m = 0; m < 8; ++m)
; #pragma unroll
;             for (int n = 0; n < 4; ++n) acc[m][n] = mfma16(bfr[n], af[m], acc[m][n]);
;         __builtin_amdgcn_s_setprio(0);
;         asm volatile("s_waitcnt vmcnt(0)" ::: "memory");
;         __syncthreads();
;     }
.Lmy_p_loop:
	s_waitcnt vmcnt(0)
	s_barrier
	ds_read_b128 v[130:133], v233
	ds_read_b128 v[134:137], v233 offset:2048
	ds_read_b128 v[138:141], v233 offset:4096
	ds_read_b128 v[142:145], v233 offset:6144
	ds_read_b128 v[146:149], v234
	ds_read_b128 v[150:153], v234 offset:2048
	ds_read_b128 v[154:157], v234 offset:4096
	ds_read_b128 v[158:161], v234 offset:6144
	ds_read_b128 v[162:165], v231
	ds_read_b128 v[166:169], v231 offset:2048
	ds_read_b128 v[170:173], v231 offset:4096
	ds_read_b128 v[174:177], v231 offset:6144
	ds_read_b128 v[182:185], v231 offset:8192
	ds_read_b128 v[186:189], v231 offset:10240
	ds_read_b128 v[190:193], v231 offset:12288
	ds_read_b128 v[194:197], v231 offset:14336
	ds_read_b128 v[198:201], v232
	ds_read_b128 v[202:205], v232 offset:2048
	ds_read_b128 v[206:209], v232 offset:4096
	ds_read_b128 v[210:213], v232 offset:6144
	ds_read_b128 v[214:217], v232 offset:8192
	ds_read_b128 v[218:221], v232 offset:10240
	ds_read_b128 v[222:225], v232 offset:12288
	ds_read_b128 v[226:229], v232 offset:14336
	s_add_u32 s42, s42, 0x80
	s_addc_u32 s43, s43, 0
	s_add_u32 s44, s44, 0x80
	s_addc_u32 s45, s45, 0
	s_waitcnt lgkmcnt(0)
	s_barrier
	s_setprio 1
	v_mfma_f32_16x16x32_bf16 v[126:129], v[130:133], v[162:165], v[126:129]
	v_mfma_f32_16x16x32_bf16 v[122:125], v[134:137], v[162:165], v[122:125]
	v_mfma_f32_16x16x32_bf16 v[118:121], v[138:141], v[162:165], v[118:121]
	v_mfma_f32_16x16x32_bf16 v[114:117], v[142:145], v[162:165], v[114:117]
	s_add_i32 m0, s28, 0x0
	s_add_u32 s26, s42, 0x0
	s_addc_u32 s27, s43, 0
	global_load_lds_dwordx4 v230, s[26:27]
	v_mfma_f32_16x16x32_bf16 v[110:113], v[130:133], v[166:169], v[110:113]
	v_mfma_f32_16x16x32_bf16 v[106:109], v[134:137], v[166:169], v[106:109]
	v_mfma_f32_16x16x32_bf16 v[102:105], v[138:141], v[166:169], v[102:105]
	v_mfma_f32_16x16x32_bf16 v[98:101], v[142:145], v[166:169], v[98:101]
	s_add_i32 m0, s28, 0x1000
	s_add_u32 s26, s42, 0x10000
	s_addc_u32 s27, s43, 0
	global_load_lds_dwordx4 v230, s[26:27]
	v_mfma_f32_16x16x32_bf16 v[94:97], v[130:133], v[170:173], v[94:97]
	v_mfma_f32_16x16x32_bf16 v[90:93], v[134:137], v[170:173], v[90:93]
	v_mfma_f32_16x16x32_bf16 v[86:89], v[138:141], v[170:173], v[86:89]
	v_mfma_f32_16x16x32_bf16 v[82:85], v[142:145], v[170:173], v[82:85]
	s_add_i32 m0, s28, 0x2000
	s_add_u32 s26, s42, 0x20000
	s_addc_u32 s27, s43, 0
	global_load_lds_dwordx4 v230, s[26:27]
	v_mfma_f32_16x16x32_bf16 v[78:81], v[130:133], v[174:177], v[78:81]
	v_mfma_f32_16x16x32_bf16 v[74:77], v[134:137], v[174:177], v[74:77]
	v_mfma_f32_16x16x32_bf16 v[70:73], v[138:141], v[174:177], v[70:73]
	v_mfma_f32_16x16x32_bf16 v[66:69], v[142:145], v[174:177], v[66:69]
	s_add_i32 m0, s28, 0x3000
	s_add_u32 s26, s42, 0x30000
	s_addc_u32 s27, s43, 0
	global_load_lds_dwordx4 v230, s[26:27]
	v_mfma_f32_16x16x32_bf16 v[62:65], v[130:133], v[182:185], v[62:65]
	v_mfma_f32_16x16x32_bf16 v[58:61], v[134:137], v[182:185], v[58:61]
	v_mfma_f32_16x16x32_bf16 v[54:57], v[138:141], v[182:185], v[54:57]
	v_mfma_f32_16x16x32_bf16 v[50:53], v[142:145], v[182:185], v[50:53]
	s_add_i32 m0, s28, 0x4000
	s_add_u32 s26, s42, 0x40000
	s_addc_u32 s27, s43, 0
	global_load_lds_dwordx4 v230, s[26:27]
	v_mfma_f32_16x16x32_bf16 v[46:49], v[130:133], v[186:189], v[46:49]
	v_mfma_f32_16x16x32_bf16 v[42:45], v[134:137], v[186:189], v[42:45]
	v_mfma_f32_16x16x32_bf16 v[38:41], v[138:141], v[186:189], v[38:41]
	v_mfma_f32_16x16x32_bf16 v[34:37], v[142:145], v[186:189], v[34:37]
	s_add_i32 m0, s28, 0x5000
	s_add_u32 s26, s42, 0x50000
	s_addc_u32 s27, s43, 0
	global_load_lds_dwordx4 v230, s[26:27]
	v_mfma_f32_16x16x32_bf16 v[30:33], v[130:133], v[190:193], v[30:33]
	v_mfma_f32_16x16x32_bf16 v[26:29], v[134:137], v[190:193], v[26:29]
	v_mfma_f32_16x16x32_bf16 v[22:25], v[138:141], v[190:193], v[22:25]
	v_mfma_f32_16x16x32_bf16 v[18:21], v[142:145], v[190:193], v[18:21]
	s_add_i32 m0, s28, 0x6000
	s_add_u32 s26, s42, 0x60000
	s_addc_u32 s27, s43, 0
	global_load_lds_dwordx4 v230, s[26:27]
	v_mfma_f32_16x16x32_bf16 v[14:17], v[130:133], v[194:197], v[14:17]
	v_mfma_f32_16x16x32_bf16 v[10:13], v[134:137], v[194:197], v[10:13]
	v_mfma_f32_16x16x32_bf16 v[6:9], v[138:141], v[194:197], v[6:9]
	v_mfma_f32_16x16x32_bf16 v[2:5], v[142:145], v[194:197], v[2:5]
	s_add_i32 m0, s28, 0x7000
	s_add_u32 s26, s42, 0x70000
	s_addc_u32 s27, s43, 0
	global_load_lds_dwordx4 v230, s[26:27]
	v_mfma_f32_16x16x32_bf16 v[126:129], v[146:149], v[198:201], v[126:129]
	v_mfma_f32_16x16x32_bf16 v[122:125], v[150:153], v[198:201], v[122:125]
	v_mfma_f32_16x16x32_bf16 v[118:121], v[154:157], v[198:201], v[118:121]
	v_mfma_f32_16x16x32_bf16 v[114:117], v[158:161], v[198:201], v[114:117]
	s_add_i32 m0, s28, 0x8000
	s_add_u32 s26, s44, 0x0
	s_addc_u32 s27, s45, 0
	global_load_lds_dwordx4 v230, s[26:27]
	v_mfma_f32_16x16x32_bf16 v[110:113], v[146:149], v[202:205], v[110:113]
	v_mfma_f32_16x16x32_bf16 v[106:109], v[150:153], v[202:205], v[106:109]
	v_mfma_f32_16x16x32_bf16 v[102:105], v[154:157], v[202:205], v[102:105]
	v_mfma_f32_16x16x32_bf16 v[98:101], v[158:161], v[202:205], v[98:101]
	s_add_i32 m0, s28, 0x9000
	s_add_u32 s26, s44, 0x10000
	s_addc_u32 s27, s45, 0
	global_load_lds_dwordx4 v230, s[26:27]
	v_mfma_f32_16x16x32_bf16 v[94:97], v[146:149], v[206:209], v[94:97]
	v_mfma_f32_16x16x32_bf16 v[90:93], v[150:153], v[206:209], v[90:93]
	v_mfma_f32_16x16x32_bf16 v[86:89], v[154:157], v[206:209], v[86:89]
	v_mfma_f32_16x16x32_bf16 v[82:85], v[158:161], v[206:209], v[82:85]
	s_add_i32 m0, s28, 0xa000
	s_add_u32 s26, s44, 0x20000
	s_addc_u32 s27, s45, 0
	global_load_lds_dwordx4 v230, s[26:27]
	v_mfma_f32_16x16x32_bf16 v[78:81], v[146:149], v[210:213], v[78:81]
; __device__ __forceinline__ f32x4 mfma16(bf16x8 a, bf16x8 b, f32x4 c) { return __builtin_amdgcn_mfma_f32_16x16x32_bf16(a, b, c, 0, 0, 0); }
; __device__ __forceinline__ void gemm_acc2(const bf16_t* __restrict__ A, long lda, const bf16_t* __restrict__ Bt, long ldb, int K, f32x4 (&acc)[8][4], char* lds) {
;     ...
;     for (int kt = 0; kt < nk; ++kt) {
;         char* cur = lds + (kt & 1) * 24576;
;         if (kt + 1 < nk) gemm2_stage(A, lda, Bt, ldb, kt + 1, lds + ((kt + 1) & 1) * 24576, tid);
;         bf16x8 bfr[4];
; #pragma unroll
;         for (int n = 0; n < 4; ++n) { const int row = wc * 64 + n * 16 + fr; bfr[n] = *reinterpret_cast<const bf16x8*>(cur + 16384 + row * 64 + ((fq ^ ((row >> 2) & 3)) << 4)); }
;         bf16x8 af[8];
; #pragma unroll
;         for (int m = 0; m < 8; ++m) { const int row = wr * 128 + m * 16 + fr; af[m] = *reinterpret_cast<const bf16x8*>(cur + row * 64 + ((fq ^ ((row >> 2) & 3)) << 4)); }
;         __builtin_amdgcn_s_setprio(1);
; #pragma unroll
;         for (int m = 0; m < 8; ++m)
; #pragma unroll
;             for (int n = 0; n < 4; ++n) acc[m][n] = mfma16(bfr[n], af[m], acc[m][n]);
;         __builtin_amdgcn_s_setprio(0);
;         asm volatile("s_waitcnt vmcnt(0)" ::: "memory");
;         __syncthreads();
;     }
	v_mfma_f32_16x16x32_bf16 v[74:77], v[150:153], v[210:213], v[74:77]
	v_mfma_f32_16x16x32_bf16 v[70:73], v[154:157], v[210:213], v[70:73]
	v_mfma_f32_16x16x32_bf16 v[66:69], v[158:161], v[210:213], v[66:69]
	s_add_i32 m0, s28, 0xb000
	s_add_u32 s26, s44, 0x30000
	s_addc_u32 s27, s45, 0
	global_load_lds_dwordx4 v230, s[26:27]
	v_mfma_f32_16x16x32_bf16 v[62:65], v[146:149], v[214:217], v[62:65]
	v_mfma_f32_16x16x32_bf16 v[58:61], v[150:153], v[214:217], v[58:61]
	v_mfma_f32_16x16x32_bf16 v[54:57], v[154:157], v[214:217], v[54:57]
	v_mfma_f32_16x16x32_bf16 v[50:53], v[158:161], v[214:217], v[50:53]
	v_mfma_f32_16x16x32_bf16 v[46:49], v[146:149], v[218:221], v[46:49]
	v_mfma_f32_16x16x32_bf16 v[42:45], v[150:153], v[218:221], v[42:45]
	v_mfma_f32_16x16x32_bf16 v[38:41], v[154:157], v[218:221], v[38:41]
	v_mfma_f32_16x16x32_bf16 v[34:37], v[158:161], v[218:221], v[34:37]
	v_mfma_f32_16x16x32_bf16 v[30:33], v[146:149], v[222:225], v[30:33]
	v_mfma_f32_16x16x32_bf16 v[26:29], v[150:153], v[222:225], v[26:29]
	v_mfma_f32_16x16x32_bf16 v[22:25], v[154:157], v[222:225], v[22:25]
	v_mfma_f32_16x16x32_bf16 v[18:21], v[158:161], v[222:225], v[18:21]
	v_mfma_f32_16x16x32_bf16 v[14:17], v[146:149], v[226:229], v[14:17]
	v_mfma_f32_16x16x32_bf16 v[10:13], v[150:153], v[226:229], v[10:13]
	v_mfma_f32_16x16x32_bf16 v[6:9], v[154:157], v[226:229], v[6:9]
	v_mfma_f32_16x16x32_bf16 v[2:5], v[158:161], v[226:229], v[2:5]
	s_setprio 0
	s_add_i32 s24, s24, 1
	s_cmp_lt_u32 s24, 15
	s_cbranch_scc1 .Lmy_p_loop
	s_waitcnt vmcnt(0)
	s_barrier
; __device__ __forceinline__ f32x4 mfma16(bf16x8 a, bf16x8 b, f32x4 c) { return __builtin_amdgcn_mfma_f32_16x16x32_bf16(a, b, c, 0, 0, 0); }
; __device__ __forceinline__ void gemm_acc2(const bf16_t* __restrict__ A, long lda, const bf16_t* __restrict__ Bt, long ldb, int K, f32x4 (&acc)[8][4], char* lds) {
;     ...
;     for (int kt = 0; kt < nk; ++kt) {
;         char* cur = lds + (kt & 1) * 24576;
;         if (kt + 1 < nk) gemm2_stage(A, lda, Bt, ldb, kt + 1, lds + ((kt + 1) & 1) * 24576, tid);
;         bf16x8 bfr[4];
; #pragma unroll
;         for (int n = 0; n < 4; ++n) { const int row = wc * 64 + n * 16 + fr; bfr[n] = *reinterpret_cast<const bf16x8*>(cur + 16384 + row * 64 + ((fq ^ ((row >> 2) & 3)) << 4)); }
;         bf16x8 af[8];
; #pragma unroll
;         for (int m = 0; m < 8; ++m) { const int row = wr * 128 + m * 16 + fr; af[m] = *reinterpret_cast<const bf16x8*>(cur + row * 64 + ((fq ^ ((row >> 2) & 3)) << 4)); }
;         __builtin_amdgcn_s_setprio(1);
; #pragma unroll
;         for (int m = 0; m < 8; ++m)
; #pragma unroll
;             for (int n = 0; n < 4; ++n) acc[m][n] = mfma16(bfr[n], af[m], acc[m][n]);
;         __builtin_amdgcn_s_setprio(0);
;         asm volatile("s_waitcnt vmcnt(0)" ::: "memory");
;         __syncthreads();
;     }
; __device__ void ph_gemm_p(const Params& P, char* lds) {
;     ...
;         if (nt < 14) store_tile2_bf16(acc, prw + (size_t)mt * 256 * PRW_LD + nt * 128, PRW_LD);
;         else store_tile2_bf16(acc, prest + (size_t)mt * 256 * PREST_LD + (nt - 14) * 128, PREST_LD);
	ds_read_b128 v[130:133], v233
	ds_read_b128 v[134:137], v233 offset:2048
	ds_read_b128 v[138:141], v233 offset:4096
	ds_read_b128 v[142:145], v233 offset:6144
	ds_read_b128 v[146:149], v234
	ds_read_b128 v[150:153], v234 offset:2048
	ds_read_b128 v[154:157], v234 offset:4096
	ds_read_b128 v[158:161], v234 offset:6144
	ds_read_b128 v[162:165], v231
	ds_read_b128 v[166:169], v231 offset:2048
	ds_read_b128 v[170:173], v231 offset:4096
	ds_read_b128 v[174:177], v231 offset:6144
	ds_read_b128 v[182:185], v231 offset:8192
	ds_read_b128 v[186:189], v231 offset:10240
	ds_read_b128 v[190:193], v231 offset:12288
	ds_read_b128 v[194:197], v231 offset:14336
	ds_read_b128 v[198:201], v232
	ds_read_b128 v[202:205], v232 offset:2048
	ds_read_b128 v[206:209], v232 offset:4096
	ds_read_b128 v[210:213], v232 offset:6144
	ds_read_b128 v[214:217], v232 offset:8192
	ds_read_b128 v[218:221], v232 offset:10240
	ds_read_b128 v[222:225], v232 offset:12288
	ds_read_b128 v[226:229], v232 offset:14336
	s_waitcnt lgkmcnt(0)
	s_setprio 1
	v_mfma_f32_16x16x32_bf16 v[126:129], v[130:133], v[162:165], v[126:129]
	v_mfma_f32_16x16x32_bf16 v[122:125], v[134:137], v[162:165], v[122:125]
	v_mfma_f32_16x16x32_bf16 v[118:121], v[138:141], v[162:165], v[118:121]
	v_mfma_f32_16x16x32_bf16 v[114:117], v[142:145], v[162:165], v[114:117]
	v_mfma_f32_16x16x32_bf16 v[110:113], v[130:133], v[166:169], v[110:113]
	v_mfma_f32_16x16x32_bf16 v[106:109], v[134:137], v[166:169], v[106:109]
	v_mfma_f32_16x16x32_bf16 v[102:105], v[138:141], v[166:169], v[102:105]
	v_mfma_f32_16x16x32_bf16 v[98:101], v[142:145], v[166:169], v[98:101]
	v_mfma_f32_16x16x32_bf16 v[94:97], v[130:133], v[170:173], v[94:97]
	v_mfma_f32_16x16x32_bf16 v[90:93], v[134:137], v[170:173], v[90:93]
	v_mfma_f32_16x16x32_bf16 v[86:89], v[138:141], v[170:173], v[86:89]
	v_mfma_f32_16x16x32_bf16 v[82:85], v[142:145], v[170:173], v[82:85]
	v_mfma_f32_16x16x32_bf16 v[78:81], v[130:133], v[174:177], v[78:81]
	v_mfma_f32_16x16x32_bf16 v[74:77], v[134:137], v[174:177], v[74:77]
	v_mfma_f32_16x16x32_bf16 v[70:73], v[138:141], v[174:177], v[70:73]
	v_mfma_f32_16x16x32_bf16 v[66:69], v[142:145], v[174:177], v[66:69]
	v_mfma_f32_16x16x32_bf16 v[62:65], v[130:133], v[182:185], v[62:65]
	v_mfma_f32_16x16x32_bf16 v[58:61], v[134:137], v[182:185], v[58:61]
	v_mfma_f32_16x16x32_bf16 v[54:57], v[138:141], v[182:185], v[54:57]
	v_mfma_f32_16x16x32_bf16 v[50:53], v[142:145], v[182:185], v[50:53]
	v_mfma_f32_16x16x32_bf16 v[46:49], v[130:133], v[186:189], v[46:49]
	v_mfma_f32_16x16x32_bf16 v[42:45], v[134:137], v[186:189], v[42:45]
	v_mfma_f32_16x16x32_bf16 v[38:41], v[138:141], v[186:189], v[38:41]
	v_mfma_f32_16x16x32_bf16 v[34:37], v[142:145], v[186:189], v[34:37]
	v_mfma_f32_16x16x32_bf16 v[30:33], v[130:133], v[190:193], v[30:33]
	v_mfma_f32_16x16x32_bf16 v[26:29], v[134:137], v[190:193], v[26:29]
	v_mfma_f32_16x16x32_bf16 v[22:25], v[138:141], v[190:193], v[22:25]
	v_mfma_f32_16x16x32_bf16 v[18:21], v[142:145], v[190:193], v[18:21]
	v_mfma_f32_16x16x32_bf16 v[14:17], v[130:133], v[194:197], v[14:17]
	v_mfma_f32_16x16x32_bf16 v[10:13], v[134:137], v[194:197], v[10:13]
	v_mfma_f32_16x16x32_bf16 v[6:9], v[138:141], v[194:197], v[6:9]
	v_mfma_f32_16x16x32_bf16 v[2:5], v[142:145], v[194:197], v[2:5]
	v_mfma_f32_16x16x32_bf16 v[126:129], v[146:149], v[198:201], v[126:129]
	v_mfma_f32_16x16x32_bf16 v[122:125], v[150:153], v[198:201], v[122:125]
	v_mfma_f32_16x16x32_bf16 v[118:121], v[154:157], v[198:201], v[118:121]
	v_mfma_f32_16x16x32_bf16 v[114:117], v[158:161], v[198:201], v[114:117]
	v_mfma_f32_16x16x32_bf16 v[110:113], v[146:149], v[202:205], v[110:113]
	v_mfma_f32_16x16x32_bf16 v[106:109], v[150:153], v[202:205], v[106:109]
	v_mfma_f32_16x16x32_bf16 v[102:105], v[154:157], v[202:205], v[102:105]
	v_mfma_f32_16x16x32_bf16 v[98:101], v[158:161], v[202:205], v[98:101]
	v_mfma_f32_16x16x32_bf16 v[94:97], v[146:149], v[206:209], v[94:97]
	v_mfma_f32_16x16x32_bf16 v[90:93], v[150:153], v[206:209], v[90:93]
	v_mfma_f32_16x16x32_bf16 v[86:89], v[154:157], v[206:209], v[86:89]
	v_mfma_f32_16x16x32_bf16 v[82:85], v[158:161], v[206:209], v[82:85]
	v_mfma_f32_16x16x32_bf16 v[78:81], v[146:149], v[210:213], v[78:81]
	v_mfma_f32_16x16x32_bf16 v[74:77], v[150:153], v[210:213], v[74:77]
	v_mfma_f32_16x16x32_bf16 v[70:73], v[154:157], v[210:213], v[70:73]
	v_mfma_f32_16x16x32_bf16 v[66:69], v[158:161], v[210:213], v[66:69]
	v_mfma_f32_16x16x32_bf16 v[62:65], v[146:149], v[214:217], v[62:65]
	v_mfma_f32_16x16x32_bf16 v[58:61], v[150:153], v[214:217], v[58:61]
	v_mfma_f32_16x16x32_bf16 v[54:57], v[154:157], v[214:217], v[54:57]
	v_mfma_f32_16x16x32_bf16 v[50:53], v[158:161], v[214:217], v[50:53]
	v_mfma_f32_16x16x32_bf16 v[46:49], v[146:149], v[218:221], v[46:49]
	v_mfma_f32_16x16x32_bf16 v[42:45], v[150:153], v[218:221], v[42:45]
	v_mfma_f32_16x16x32_bf16 v[38:41], v[154:157], v[218:221], v[38:41]
	v_mfma_f32_16x16x32_bf16 v[34:37], v[158:161], v[218:221], v[34:37]
	v_mfma_f32_16x16x32_bf16 v[30:33], v[146:149], v[222:225], v[30:33]
	v_mfma_f32_16x16x32_bf16 v[26:29], v[150:153], v[222:225], v[26:29]
	v_mfma_f32_16x16x32_bf16 v[22:25], v[154:157], v[222:225], v[22:25]
	v_mfma_f32_16x16x32_bf16 v[18:21], v[158:161], v[222:225], v[18:21]
	v_mfma_f32_16x16x32_bf16 v[14:17], v[146:149], v[226:229], v[14:17]
	v_mfma_f32_16x16x32_bf16 v[10:13], v[150:153], v[226:229], v[10:13]
	v_mfma_f32_16x16x32_bf16 v[6:9], v[154:157], v[226:229], v[6:9]
	v_mfma_f32_16x16x32_bf16 v[2:5], v[158:161], v[226:229], v[2:5]
	s_setprio 0
	v_mov_b32_e32 v182, 0x2c60000
	v_mov_b32_e32 v183, 0x540
	v_mov_b32_e32 v184, 0x6000
	v_mov_b32_e32 v185, 0x2000
	v_mov_b32_e32 v186, 0x160000
	v_mov_b32_e32 v187, 0x70
	v_mov_b32_e32 v188, 0x1100
	v_mov_b32_e32 v218, 0
	v_mov_b32_e32 v219, 0
	v_mov_b32_e32 v220, 0
	v_mov_b32_e32 v221, 0
	s_waitcnt vmcnt(0)
	s_lshl_b32 s42, s38, 7
	s_cmp_gt_i32 s38, 13
	s_mov_b64 s[28:29], -1
	s_barrier
	s_cbranch_scc0 .LBB0_455
	s_mul_i32 s24, s0, 0x290000
	s_mul_hi_i32 s1, s0, 0x290000
	s_add_u32 s24, s74, s24
	s_mov_b32 s43, s25
	s_addc_u32 s1, s75, s1
	s_lshl_b64 s[26:27], s[42:43], 1
	s_add_u32 s24, s24, s26
	s_addc_u32 s1, s1, s27
	s_add_u32 s38, s24, 0x9fff200
	v_mov_b32_e32 v130, v178
	s_addc_u32 s39, s1, 0
	s_mov_b64 s[28:29], 0
